# E18: E14 + redundant s_setprio 0/1 pairs between the two 16-MFMA groups of each GEMM phase removed (20 pairs)
# speedup vs baseline: 1.0040x; 1.0040x over previous
; #define PG8_STAGE(bufoff, gbase, voff) do { _Pragma("unroll") for (int _i = 0; _i < 2; ++_i) \
;         __builtin_amdgcn_global_load_lds((const unsigned*)((const char*)(gbase) + (voff)[_i]), (LAS unsigned*)(lds + (bufoff) + ldsw + _i * 8192), 16, 0, 0); } while (0)
; #define PG8_LDA(dst, b, h) do { _Pragma("unroll") for (int m = 0; m < 4; ++m) _Pragma("unroll") for (int k = 0; k < 2; ++k) dst[m][k] = *(const LAS bf16x8*)(lds + PG8_SA(b, h) + aoff + m * 2048 + k * 1024); } while (0)
; #define PG8_LDB(dst, b, h) do { _Pragma("unroll") for (int n = 0; n < 2; ++n) _Pragma("unroll") for (int k = 0; k < 2; ++k) dst[n][k] = *(const LAS bf16x8*)(lds + PG8_SB(b, h) + boff + n * 2048 + k * 1024); } while (0)
; #define PG8_MMA(ai, bj, At, Bt) do { __builtin_amdgcn_s_setprio(1); _Pragma("unroll") for (int m = 0; m < 4; ++m) _Pragma("unroll") for (int n = 0; n < 2; ++n) _Pragma("unroll") for (int k = 0; k < 2; ++k) \
;         acc[ai][bj][m][n] = __builtin_amdgcn_mfma_f32_16x16x32_bf16(Bt[n][k], At[m][k], acc[ai][bj][m][n], 0, 0, 0); __builtin_amdgcn_s_setprio(0); } while (0)
; #define PG8_WAIT_V(n) asm volatile("s_waitcnt vmcnt(" #n ")" ::: "memory")
; #define PG8_WAIT_L(n) asm volatile("s_waitcnt lgkmcnt(" #n ")" ::: "memory")
; #define PG8_BAR __builtin_amdgcn_s_barrier()
; #define PG8_SCHED __builtin_amdgcn_sched_barrier(0)
; template <class Epi>
; __device__ __forceinline__ void gemm_phase(LAS unsigned char* lds, const Gemm g, const StaticOrder& S, const Epi& E) {
;     ...
;         for (int t = 0; t < nt; t += 2) {
;             const bool last = (t == nt - 2);
;             const char* a1 = cA + (size_t)(t + 1) * kstep;
;             const char* a2 = last ? nA : cA + (size_t)(t + 2) * kstep; const char* b2 = last ? nB : cB + (size_t)(t + 2) * kstep;
;             const char* a3 = a2 + kstep; const char* b3 = b2 + kstep;
;             PG8_LDB(B0, 0, 0); PG8_LDB(B1, 0, 1); PG8_SCHED; PG8_LDA(At, 0, 0); PG8_STAGE(PG8_SA(1, 1), a1 + hstep, voffA);
;             PG8_WAIT_V(8); PG8_WAIT_L(0); PG8_BAR; PG8_MMA(0, 0, At, B0); PG8_MMA(0, 1, At, B1); PG8_BAR; PG8_SCHED;
;             PG8_LDA(At, 0, 1); PG8_STAGE(PG8_SB(0, 0), b2, voffB); PG8_STAGE(PG8_SB(0, 1), b2 + hstep, voffB); PG8_STAGE(PG8_SA(0, 0), a2, voffA);
;             PG8_WAIT_V(8); PG8_WAIT_L(0); PG8_BAR; PG8_MMA(1, 0, At, B0); PG8_MMA(1, 1, At, B1); PG8_BAR; PG8_SCHED;
.LBB0_191:
	s_add_u32 s22, s20, 0xfff80080
	s_addc_u32 s23, s21, -1
	s_add_i32 s55, 0, 0x10000
	s_cmp_eq_u32 s45, 28
	s_cselect_b32 s25, s15, s23
	s_cselect_b32 s24, s39, s22
	s_cselect_b32 s23, s13, s44
	s_cselect_b32 s22, s40, s41
	s_add_i32 s76, 0, 0x14000
	s_waitcnt lgkmcnt(0)
	v_add_u32_e32 v170, s55, v147
	v_add_u32_e32 v186, s76, v147
	ds_read_b128 v[132:135], v170
	ds_read_b128 v[162:165], v170 offset:1024
	ds_read_b128 v[166:169], v170 offset:2048
	ds_read_b128 v[170:173], v170 offset:3072
	ds_read_b128 v[174:177], v186
	ds_read_b128 v[178:181], v186 offset:1024
	ds_read_b128 v[182:185], v186 offset:2048
	ds_read_b128 v[186:189], v186 offset:3072
	v_lshl_add_u64 v[242:243], s[20:21], 0, v[158:159]
	s_add_i32 m0, s29, 0xc000
	ds_read_b128 v[190:193], v213
	ds_read_b128 v[214:217], v213 offset:1024
	ds_read_b128 v[218:221], v213 offset:2048
	ds_read_b128 v[222:225], v213 offset:3072
	ds_read_b128 v[226:229], v213 offset:4096
	ds_read_b128 v[230:233], v213 offset:5120
	ds_read_b128 v[234:237], v213 offset:6144
	ds_read_b128 v[238:241], v213 offset:7168
	global_load_lds_dwordx4 v[242:243], off
	v_lshl_add_u64 v[242:243], s[20:21], 0, v[160:161]
	s_add_i32 m0, s29, 0xe000
	s_nop 0
	global_load_lds_dwordx4 v[242:243], off
	s_waitcnt vmcnt(8)
	s_waitcnt lgkmcnt(0)
	s_barrier
	s_setprio 1
	s_waitcnt lgkmcnt(0)
	v_mfma_f32_16x16x32_bf16 v[128:131], v[132:135], v[190:193], v[128:131]
	v_mfma_f32_16x16x32_bf16 v[124:127], v[166:169], v[190:193], v[124:127]
	v_mfma_f32_16x16x32_bf16 v[112:115], v[132:135], v[218:221], v[112:115]
	v_mfma_f32_16x16x32_bf16 v[108:111], v[166:169], v[218:221], v[108:111]
	v_mfma_f32_16x16x32_bf16 v[96:99], v[132:135], v[226:229], v[96:99]
	v_mfma_f32_16x16x32_bf16 v[92:95], v[166:169], v[226:229], v[92:95]
	v_mfma_f32_16x16x32_bf16 v[80:83], v[132:135], v[234:237], v[80:83]
	v_mfma_f32_16x16x32_bf16 v[76:79], v[166:169], v[234:237], v[76:79]
	v_mfma_f32_16x16x32_bf16 v[128:131], v[162:165], v[214:217], v[128:131]
	v_mfma_f32_16x16x32_bf16 v[124:127], v[170:173], v[214:217], v[124:127]
	v_mfma_f32_16x16x32_bf16 v[112:115], v[162:165], v[222:225], v[112:115]
	v_mfma_f32_16x16x32_bf16 v[108:111], v[170:173], v[222:225], v[108:111]
	v_mfma_f32_16x16x32_bf16 v[96:99], v[162:165], v[230:233], v[96:99]
	v_mfma_f32_16x16x32_bf16 v[92:95], v[170:173], v[230:233], v[92:95]
	v_mfma_f32_16x16x32_bf16 v[80:83], v[162:165], v[238:241], v[80:83]
	v_mfma_f32_16x16x32_bf16 v[76:79], v[170:173], v[238:241], v[76:79]
	v_mfma_f32_16x16x32_bf16 v[120:123], v[174:177], v[190:193], v[120:123]
	v_mfma_f32_16x16x32_bf16 v[116:119], v[182:185], v[190:193], v[116:119]
	v_mfma_f32_16x16x32_bf16 v[104:107], v[174:177], v[218:221], v[104:107]
	v_mfma_f32_16x16x32_bf16 v[100:103], v[182:185], v[218:221], v[100:103]
	v_mfma_f32_16x16x32_bf16 v[88:91], v[174:177], v[226:229], v[88:91]
	v_mfma_f32_16x16x32_bf16 v[84:87], v[182:185], v[226:229], v[84:87]
	v_mfma_f32_16x16x32_bf16 v[72:75], v[174:177], v[234:237], v[72:75]
	v_mfma_f32_16x16x32_bf16 v[68:71], v[182:185], v[234:237], v[68:71]
	v_mfma_f32_16x16x32_bf16 v[120:123], v[178:181], v[214:217], v[120:123]
	v_mfma_f32_16x16x32_bf16 v[116:119], v[186:189], v[214:217], v[116:119]
	v_mfma_f32_16x16x32_bf16 v[104:107], v[178:181], v[222:225], v[104:107]
	v_mfma_f32_16x16x32_bf16 v[100:103], v[186:189], v[222:225], v[100:103]
	v_mfma_f32_16x16x32_bf16 v[88:91], v[178:181], v[230:233], v[88:91]
	v_mfma_f32_16x16x32_bf16 v[84:87], v[186:189], v[230:233], v[84:87]
	v_mfma_f32_16x16x32_bf16 v[72:75], v[178:181], v[238:241], v[72:75]
	v_mfma_f32_16x16x32_bf16 v[68:71], v[186:189], v[238:241], v[68:71]
	s_setprio 0
	s_barrier
	s_add_i32 s55, s55, s28
	v_lshl_add_u64 v[242:243], s[22:23], 0, v[140:141]
	s_mov_b32 m0, s55
	ds_read_b128 v[190:193], v213 offset:16384
	ds_read_b128 v[214:217], v213 offset:17408
	ds_read_b128 v[218:221], v213 offset:18432
	ds_read_b128 v[222:225], v213 offset:19456
	ds_read_b128 v[226:229], v213 offset:20480
	ds_read_b128 v[230:233], v213 offset:21504
	ds_read_b128 v[234:237], v213 offset:22528
	ds_read_b128 v[238:241], v213 offset:23552
	global_load_lds_dwordx4 v[242:243], off
	s_add_i32 m0, s55, 0x2000
	s_add_u32 s74, s22, 0x80000
	v_lshl_add_u64 v[244:245], s[22:23], 0, v[136:137]
	s_addc_u32 s75, s23, 0
	s_add_i32 s55, s76, s28
	global_load_lds_dwordx4 v[244:245], off
	v_lshl_add_u64 v[246:247], s[74:75], 0, v[140:141]
	s_mov_b32 m0, s55
	v_lshl_add_u64 v[248:249], s[24:25], 0, v[138:139]
	global_load_lds_dwordx4 v[246:247], off
	v_lshl_add_u64 v[246:247], s[74:75], 0, v[136:137]
	s_add_i32 m0, s55, 0x2000
	s_nop 0
	global_load_lds_dwordx4 v[246:247], off
	v_lshl_add_u64 v[246:247], s[24:25], 0, v[156:157]
	s_mov_b32 m0, s29
	s_nop 0
	global_load_lds_dwordx4 v[246:247], off
	s_mov_b32 m0, s30
	s_nop 0
	global_load_lds_dwordx4 v[248:249], off
	s_waitcnt vmcnt(8)
	s_waitcnt lgkmcnt(0)
	s_barrier
; #define PG8_STAGE(bufoff, gbase, voff) do { _Pragma("unroll") for (int _i = 0; _i < 2; ++_i) \
;         __builtin_amdgcn_global_load_lds((const unsigned*)((const char*)(gbase) + (voff)[_i]), (LAS unsigned*)(lds + (bufoff) + ldsw + _i * 8192), 16, 0, 0); } while (0)
; #define PG8_LDA(dst, b, h) do { _Pragma("unroll") for (int m = 0; m < 4; ++m) _Pragma("unroll") for (int k = 0; k < 2; ++k) dst[m][k] = *(const LAS bf16x8*)(lds + PG8_SA(b, h) + aoff + m * 2048 + k * 1024); } while (0)
; #define PG8_LDB(dst, b, h) do { _Pragma("unroll") for (int n = 0; n < 2; ++n) _Pragma("unroll") for (int k = 0; k < 2; ++k) dst[n][k] = *(const LAS bf16x8*)(lds + PG8_SB(b, h) + boff + n * 2048 + k * 1024); } while (0)
; #define PG8_MMA(ai, bj, At, Bt) do { __builtin_amdgcn_s_setprio(1); _Pragma("unroll") for (int m = 0; m < 4; ++m) _Pragma("unroll") for (int n = 0; n < 2; ++n) _Pragma("unroll") for (int k = 0; k < 2; ++k) \
;         acc[ai][bj][m][n] = __builtin_amdgcn_mfma_f32_16x16x32_bf16(Bt[n][k], At[m][k], acc[ai][bj][m][n], 0, 0, 0); __builtin_amdgcn_s_setprio(0); } while (0)
; #define PG8_WAIT_V(n) asm volatile("s_waitcnt vmcnt(" #n ")" ::: "memory")
; #define PG8_WAIT_L(n) asm volatile("s_waitcnt lgkmcnt(" #n ")" ::: "memory")
; #define PG8_BAR __builtin_amdgcn_s_barrier()
; #define PG8_SCHED __builtin_amdgcn_sched_barrier(0)
; template <class Epi>
; __device__ __forceinline__ void gemm_phase(LAS unsigned char* lds, const Gemm g, const StaticOrder& S, const Epi& E) {
;     ...
;             PG8_LDA(At, 0, 1); PG8_STAGE(PG8_SB(0, 0), b2, voffB); PG8_STAGE(PG8_SB(0, 1), b2 + hstep, voffB); PG8_STAGE(PG8_SA(0, 0), a2, voffA);
;             PG8_WAIT_V(8); PG8_WAIT_L(0); PG8_BAR; PG8_MMA(1, 0, At, B0); PG8_MMA(1, 1, At, B1); PG8_BAR; PG8_SCHED;
;             PG8_LDB(B0, 1, 0); PG8_LDB(B1, 1, 1); PG8_SCHED; PG8_LDA(At, 1, 0); PG8_STAGE(PG8_SA(0, 1), a2 + hstep, voffA);
;             PG8_WAIT_V(8); PG8_WAIT_L(0); PG8_BAR; PG8_MMA(0, 0, At, B0); PG8_MMA(0, 1, At, B1); PG8_BAR; PG8_SCHED;
	s_setprio 1
	s_waitcnt lgkmcnt(0)
	v_mfma_f32_16x16x32_bf16 v[64:67], v[132:135], v[190:193], v[64:67]
	v_mfma_f32_16x16x32_bf16 v[60:63], v[166:169], v[190:193], v[60:63]
	v_mfma_f32_16x16x32_bf16 v[48:51], v[132:135], v[218:221], v[48:51]
	v_mfma_f32_16x16x32_bf16 v[44:47], v[166:169], v[218:221], v[44:47]
	v_mfma_f32_16x16x32_bf16 v[32:35], v[132:135], v[226:229], v[32:35]
	v_mfma_f32_16x16x32_bf16 v[28:31], v[166:169], v[226:229], v[28:31]
	v_mfma_f32_16x16x32_bf16 v[16:19], v[132:135], v[234:237], v[16:19]
	v_mfma_f32_16x16x32_bf16 v[12:15], v[166:169], v[234:237], v[12:15]
	v_mfma_f32_16x16x32_bf16 v[64:67], v[162:165], v[214:217], v[64:67]
	v_mfma_f32_16x16x32_bf16 v[60:63], v[170:173], v[214:217], v[60:63]
	v_mfma_f32_16x16x32_bf16 v[48:51], v[162:165], v[222:225], v[48:51]
	v_mfma_f32_16x16x32_bf16 v[44:47], v[170:173], v[222:225], v[44:47]
	v_mfma_f32_16x16x32_bf16 v[32:35], v[162:165], v[230:233], v[32:35]
	v_mfma_f32_16x16x32_bf16 v[28:31], v[170:173], v[230:233], v[28:31]
	v_mfma_f32_16x16x32_bf16 v[16:19], v[162:165], v[238:241], v[16:19]
	v_mfma_f32_16x16x32_bf16 v[12:15], v[170:173], v[238:241], v[12:15]
	v_mfma_f32_16x16x32_bf16 v[56:59], v[174:177], v[190:193], v[56:59]
	v_mfma_f32_16x16x32_bf16 v[52:55], v[182:185], v[190:193], v[52:55]
	v_mfma_f32_16x16x32_bf16 v[40:43], v[174:177], v[218:221], v[40:43]
	v_mfma_f32_16x16x32_bf16 v[36:39], v[182:185], v[218:221], v[36:39]
	v_mfma_f32_16x16x32_bf16 v[24:27], v[174:177], v[226:229], v[24:27]
	v_mfma_f32_16x16x32_bf16 v[20:23], v[182:185], v[226:229], v[20:23]
	v_mfma_f32_16x16x32_bf16 v[8:11], v[174:177], v[234:237], v[8:11]
	v_mfma_f32_16x16x32_bf16 v[4:7], v[182:185], v[234:237], v[4:7]
	v_mfma_f32_16x16x32_bf16 v[56:59], v[178:181], v[214:217], v[56:59]
	v_mfma_f32_16x16x32_bf16 v[52:55], v[186:189], v[214:217], v[52:55]
	v_mfma_f32_16x16x32_bf16 v[40:43], v[178:181], v[222:225], v[40:43]
	v_mfma_f32_16x16x32_bf16 v[36:39], v[186:189], v[222:225], v[36:39]
	v_mfma_f32_16x16x32_bf16 v[24:27], v[178:181], v[230:233], v[24:27]
	v_mfma_f32_16x16x32_bf16 v[20:23], v[186:189], v[230:233], v[20:23]
	v_mfma_f32_16x16x32_bf16 v[8:11], v[178:181], v[238:241], v[8:11]
	v_mfma_f32_16x16x32_bf16 v[4:7], v[186:189], v[238:241], v[4:7]
	s_setprio 0
	s_barrier
	s_add_i32 s55, 0, 0x18000
	s_add_i32 s74, 0, 0x1c000
	v_add_u32_e32 v170, s55, v147
	v_add_u32_e32 v186, s74, v147
	ds_read_b128 v[132:135], v170
	ds_read_b128 v[162:165], v170 offset:1024
	ds_read_b128 v[166:169], v170 offset:2048
	ds_read_b128 v[170:173], v170 offset:3072
	ds_read_b128 v[174:177], v186
	ds_read_b128 v[178:181], v186 offset:1024
	ds_read_b128 v[182:185], v186 offset:2048
	ds_read_b128 v[186:189], v186 offset:3072
	s_add_u32 s24, s24, 0x80000
	s_addc_u32 s25, s25, 0
	s_mov_b32 m0, s31
	v_lshl_add_u64 v[250:251], s[24:25], 0, v[156:157]
	ds_read_b128 v[190:193], v213 offset:32768
	ds_read_b128 v[214:217], v213 offset:33792
	ds_read_b128 v[218:221], v213 offset:34816
	ds_read_b128 v[222:225], v213 offset:35840
	ds_read_b128 v[226:229], v213 offset:36864
	ds_read_b128 v[230:233], v213 offset:37888
	ds_read_b128 v[234:237], v213 offset:38912
	ds_read_b128 v[238:241], v213 offset:39936
	global_load_lds_dwordx4 v[250:251], off
	v_lshl_add_u64 v[250:251], s[24:25], 0, v[138:139]
	s_mov_b32 m0, s34
	s_nop 0
	global_load_lds_dwordx4 v[250:251], off
	s_waitcnt vmcnt(8)
	s_waitcnt lgkmcnt(0)
	s_barrier
	s_setprio 1
	s_waitcnt lgkmcnt(0)
	v_mfma_f32_16x16x32_bf16 v[128:131], v[132:135], v[190:193], v[128:131]
	v_mfma_f32_16x16x32_bf16 v[124:127], v[166:169], v[190:193], v[124:127]
	v_mfma_f32_16x16x32_bf16 v[112:115], v[132:135], v[218:221], v[112:115]
	v_mfma_f32_16x16x32_bf16 v[108:111], v[166:169], v[218:221], v[108:111]
	v_mfma_f32_16x16x32_bf16 v[96:99], v[132:135], v[226:229], v[96:99]
	v_mfma_f32_16x16x32_bf16 v[92:95], v[166:169], v[226:229], v[92:95]
	v_mfma_f32_16x16x32_bf16 v[80:83], v[132:135], v[234:237], v[80:83]
	v_mfma_f32_16x16x32_bf16 v[76:79], v[166:169], v[234:237], v[76:79]
	v_mfma_f32_16x16x32_bf16 v[128:131], v[162:165], v[214:217], v[128:131]
	v_mfma_f32_16x16x32_bf16 v[124:127], v[170:173], v[214:217], v[124:127]
	v_mfma_f32_16x16x32_bf16 v[112:115], v[162:165], v[222:225], v[112:115]
	v_mfma_f32_16x16x32_bf16 v[108:111], v[170:173], v[222:225], v[108:111]
	v_mfma_f32_16x16x32_bf16 v[96:99], v[162:165], v[230:233], v[96:99]
	v_mfma_f32_16x16x32_bf16 v[92:95], v[170:173], v[230:233], v[92:95]
	v_mfma_f32_16x16x32_bf16 v[80:83], v[162:165], v[238:241], v[80:83]
	v_mfma_f32_16x16x32_bf16 v[76:79], v[170:173], v[238:241], v[76:79]
	v_mfma_f32_16x16x32_bf16 v[120:123], v[174:177], v[190:193], v[120:123]
	v_mfma_f32_16x16x32_bf16 v[116:119], v[182:185], v[190:193], v[116:119]
	v_mfma_f32_16x16x32_bf16 v[104:107], v[174:177], v[218:221], v[104:107]
	v_mfma_f32_16x16x32_bf16 v[100:103], v[182:185], v[218:221], v[100:103]
	v_mfma_f32_16x16x32_bf16 v[88:91], v[174:177], v[226:229], v[88:91]
	v_mfma_f32_16x16x32_bf16 v[84:87], v[182:185], v[226:229], v[84:87]
	v_mfma_f32_16x16x32_bf16 v[72:75], v[174:177], v[234:237], v[72:75]
	v_mfma_f32_16x16x32_bf16 v[68:71], v[182:185], v[234:237], v[68:71]
	v_mfma_f32_16x16x32_bf16 v[120:123], v[178:181], v[214:217], v[120:123]
	v_mfma_f32_16x16x32_bf16 v[116:119], v[186:189], v[214:217], v[116:119]
	v_mfma_f32_16x16x32_bf16 v[104:107], v[178:181], v[222:225], v[104:107]
	v_mfma_f32_16x16x32_bf16 v[100:103], v[186:189], v[222:225], v[100:103]
	v_mfma_f32_16x16x32_bf16 v[88:91], v[178:181], v[230:233], v[88:91]
	v_mfma_f32_16x16x32_bf16 v[84:87], v[186:189], v[230:233], v[84:87]
	v_mfma_f32_16x16x32_bf16 v[72:75], v[178:181], v[238:241], v[72:75]
	v_mfma_f32_16x16x32_bf16 v[68:71], v[186:189], v[238:241], v[68:71]
	s_setprio 0
	s_barrier
; #define PG8_STAGE(bufoff, gbase, voff) do { _Pragma("unroll") for (int _i = 0; _i < 2; ++_i) \
;         __builtin_amdgcn_global_load_lds((const unsigned*)((const char*)(gbase) + (voff)[_i]), (LAS unsigned*)(lds + (bufoff) + ldsw + _i * 8192), 16, 0, 0); } while (0)
; #define PG8_LDA(dst, b, h) do { _Pragma("unroll") for (int m = 0; m < 4; ++m) _Pragma("unroll") for (int k = 0; k < 2; ++k) dst[m][k] = *(const LAS bf16x8*)(lds + PG8_SA(b, h) + aoff + m * 2048 + k * 1024); } while (0)
; #define PG8_MMA(ai, bj, At, Bt) do { __builtin_amdgcn_s_setprio(1); _Pragma("unroll") for (int m = 0; m < 4; ++m) _Pragma("unroll") for (int n = 0; n < 2; ++n) _Pragma("unroll") for (int k = 0; k < 2; ++k) \
;         acc[ai][bj][m][n] = __builtin_amdgcn_mfma_f32_16x16x32_bf16(Bt[n][k], At[m][k], acc[ai][bj][m][n], 0, 0, 0); __builtin_amdgcn_s_setprio(0); } while (0)
; #define PG8_WAIT_V(n) asm volatile("s_waitcnt vmcnt(" #n ")" ::: "memory")
; #define PG8_WAIT_L(n) asm volatile("s_waitcnt lgkmcnt(" #n ")" ::: "memory")
; #define PG8_BAR __builtin_amdgcn_s_barrier()
; #define PG8_SCHED __builtin_amdgcn_sched_barrier(0)
; template <class Epi>
; __device__ __forceinline__ void gemm_phase(LAS unsigned char* lds, const Gemm g, const StaticOrder& S, const Epi& E) {
;     ...
;             PG8_LDA(At, 1, 1); PG8_STAGE(PG8_SB(1, 0), b3, voffB); PG8_STAGE(PG8_SB(1, 1), b3 + hstep, voffB); PG8_STAGE(PG8_SA(1, 0), a3, voffA);
;             PG8_WAIT_V(8); PG8_WAIT_L(0); PG8_BAR; PG8_MMA(1, 0, At, B0); PG8_MMA(1, 1, At, B1); PG8_BAR; PG8_SCHED;
;         }
;         if (wr == 0) PG8_BAR;
	s_add_i32 s24, s55, s28
	v_lshl_add_u64 v[242:243], v[242:243], 0, s[68:69]
	s_mov_b32 m0, s24
	ds_read_b128 v[190:193], v213 offset:49152
	ds_read_b128 v[214:217], v213 offset:50176
	ds_read_b128 v[218:221], v213 offset:51200
	ds_read_b128 v[222:225], v213 offset:52224
	ds_read_b128 v[226:229], v213 offset:53248
	ds_read_b128 v[230:233], v213 offset:54272
	ds_read_b128 v[234:237], v213 offset:55296
	ds_read_b128 v[238:241], v213 offset:56320
	global_load_lds_dwordx4 v[242:243], off
	s_add_i32 m0, s24, 0x2000
	s_add_u32 s22, s22, 0x80080
	v_lshl_add_u64 v[242:243], v[244:245], 0, s[68:69]
	s_addc_u32 s23, s23, 0
	s_add_i32 s24, s74, s28
	global_load_lds_dwordx4 v[242:243], off
	v_lshl_add_u64 v[242:243], s[22:23], 0, v[140:141]
	s_mov_b32 m0, s24
	s_nop 0
	global_load_lds_dwordx4 v[242:243], off
	v_lshl_add_u64 v[242:243], s[22:23], 0, v[136:137]
	s_add_i32 m0, s24, 0x2000
	s_nop 0
	global_load_lds_dwordx4 v[242:243], off
	v_lshl_add_u64 v[242:243], v[246:247], 0, s[68:69]
	s_mov_b32 m0, s35
	s_nop 0
	global_load_lds_dwordx4 v[242:243], off
	v_lshl_add_u64 v[242:243], v[248:249], 0, s[68:69]
	s_mov_b32 m0, s36
	s_nop 0
	global_load_lds_dwordx4 v[242:243], off
	s_waitcnt vmcnt(8)
	s_waitcnt lgkmcnt(0)
	s_barrier
	s_setprio 1
	s_waitcnt lgkmcnt(0)
	v_mfma_f32_16x16x32_bf16 v[64:67], v[132:135], v[190:193], v[64:67]
	v_mfma_f32_16x16x32_bf16 v[60:63], v[166:169], v[190:193], v[60:63]
	v_mfma_f32_16x16x32_bf16 v[48:51], v[132:135], v[218:221], v[48:51]
	v_mfma_f32_16x16x32_bf16 v[44:47], v[166:169], v[218:221], v[44:47]
	v_mfma_f32_16x16x32_bf16 v[32:35], v[132:135], v[226:229], v[32:35]
	v_mfma_f32_16x16x32_bf16 v[28:31], v[166:169], v[226:229], v[28:31]
	v_mfma_f32_16x16x32_bf16 v[16:19], v[132:135], v[234:237], v[16:19]
	v_mfma_f32_16x16x32_bf16 v[12:15], v[166:169], v[234:237], v[12:15]
	v_mfma_f32_16x16x32_bf16 v[64:67], v[162:165], v[214:217], v[64:67]
	v_mfma_f32_16x16x32_bf16 v[60:63], v[170:173], v[214:217], v[60:63]
	v_mfma_f32_16x16x32_bf16 v[48:51], v[162:165], v[222:225], v[48:51]
	v_mfma_f32_16x16x32_bf16 v[44:47], v[170:173], v[222:225], v[44:47]
	v_mfma_f32_16x16x32_bf16 v[32:35], v[162:165], v[230:233], v[32:35]
	v_mfma_f32_16x16x32_bf16 v[28:31], v[170:173], v[230:233], v[28:31]
	v_mfma_f32_16x16x32_bf16 v[16:19], v[162:165], v[238:241], v[16:19]
	v_mfma_f32_16x16x32_bf16 v[12:15], v[170:173], v[238:241], v[12:15]
	v_mfma_f32_16x16x32_bf16 v[56:59], v[174:177], v[190:193], v[56:59]
	v_mfma_f32_16x16x32_bf16 v[52:55], v[182:185], v[190:193], v[52:55]
	v_mfma_f32_16x16x32_bf16 v[40:43], v[174:177], v[218:221], v[40:43]
	v_mfma_f32_16x16x32_bf16 v[36:39], v[182:185], v[218:221], v[36:39]
	v_mfma_f32_16x16x32_bf16 v[24:27], v[174:177], v[226:229], v[24:27]
	v_mfma_f32_16x16x32_bf16 v[20:23], v[182:185], v[226:229], v[20:23]
	v_mfma_f32_16x16x32_bf16 v[8:11], v[174:177], v[234:237], v[8:11]
	v_mfma_f32_16x16x32_bf16 v[4:7], v[182:185], v[234:237], v[4:7]
	v_mfma_f32_16x16x32_bf16 v[56:59], v[178:181], v[214:217], v[56:59]
	v_mfma_f32_16x16x32_bf16 v[52:55], v[186:189], v[214:217], v[52:55]
	v_mfma_f32_16x16x32_bf16 v[40:43], v[178:181], v[222:225], v[40:43]
	v_mfma_f32_16x16x32_bf16 v[36:39], v[186:189], v[222:225], v[36:39]
	v_mfma_f32_16x16x32_bf16 v[24:27], v[178:181], v[230:233], v[24:27]
	v_mfma_f32_16x16x32_bf16 v[20:23], v[186:189], v[230:233], v[20:23]
	v_mfma_f32_16x16x32_bf16 v[8:11], v[178:181], v[238:241], v[8:11]
	v_mfma_f32_16x16x32_bf16 v[4:7], v[186:189], v[238:241], v[4:7]
	s_setprio 0
	s_barrier
	s_add_i32 s45, s45, 2
	s_add_u32 s20, s20, 0x100
	s_addc_u32 s21, s21, 0
	s_add_u32 s41, s41, 0x100
	s_addc_u32 s44, s44, 0
	s_cmp_gt_u32 s45, 29
	s_cbranch_scc0 .LBB0_191
	s_and_b64 vcc, exec, s[10:11]
	s_cbranch_vccz .LBB0_194
	s_barrier

; #define PG8_STAGE(bufoff, gbase, voff) do { _Pragma("unroll") for (int _i = 0; _i < 2; ++_i) \
;         __builtin_amdgcn_global_load_lds((const unsigned*)((const char*)(gbase) + (voff)[_i]), (LAS unsigned*)(lds + (bufoff) + ldsw + _i * 8192), 16, 0, 0); } while (0)
; #define PG8_LDA(dst, b, h) do { _Pragma("unroll") for (int m = 0; m < 4; ++m) _Pragma("unroll") for (int k = 0; k < 2; ++k) dst[m][k] = *(const LAS bf16x8*)(lds + PG8_SA(b, h) + aoff + m * 2048 + k * 1024); } while (0)
; #define PG8_LDB(dst, b, h) do { _Pragma("unroll") for (int n = 0; n < 2; ++n) _Pragma("unroll") for (int k = 0; k < 2; ++k) dst[n][k] = *(const LAS bf16x8*)(lds + PG8_SB(b, h) + boff + n * 2048 + k * 1024); } while (0)
; #define PG8_MMA(ai, bj, At, Bt) do { __builtin_amdgcn_s_setprio(1); _Pragma("unroll") for (int m = 0; m < 4; ++m) _Pragma("unroll") for (int n = 0; n < 2; ++n) _Pragma("unroll") for (int k = 0; k < 2; ++k) \
;         acc[ai][bj][m][n] = __builtin_amdgcn_mfma_f32_16x16x32_bf16(Bt[n][k], At[m][k], acc[ai][bj][m][n], 0, 0, 0); __builtin_amdgcn_s_setprio(0); } while (0)
; #define PG8_WAIT_V(n) asm volatile("s_waitcnt vmcnt(" #n ")" ::: "memory")
; #define PG8_WAIT_L(n) asm volatile("s_waitcnt lgkmcnt(" #n ")" ::: "memory")
; #define PG8_BAR __builtin_amdgcn_s_barrier()
; #define PG8_SCHED __builtin_amdgcn_sched_barrier(0)
; template <class Epi>
; __device__ __forceinline__ void gemm_phase(LAS unsigned char* lds, const Gemm g, const StaticOrder& S, const Epi& E) {
;     ...
;         for (int t = 0; t < nt; t += 2) {
;             const bool last = (t == nt - 2);
;             const char* a1 = cA + (size_t)(t + 1) * kstep;
;             const char* a2 = last ? nA : cA + (size_t)(t + 2) * kstep; const char* b2 = last ? nB : cB + (size_t)(t + 2) * kstep;
;             const char* a3 = a2 + kstep; const char* b3 = b2 + kstep;
;             PG8_LDB(B0, 0, 0); PG8_LDB(B1, 0, 1); PG8_SCHED; PG8_LDA(At, 0, 0); PG8_STAGE(PG8_SA(1, 1), a1 + hstep, voffA);
;             PG8_WAIT_V(8); PG8_WAIT_L(0); PG8_BAR; PG8_MMA(0, 0, At, B0); PG8_MMA(0, 1, At, B1); PG8_BAR; PG8_SCHED;
;             PG8_LDA(At, 0, 1); PG8_STAGE(PG8_SB(0, 0), b2, voffB); PG8_STAGE(PG8_SB(0, 1), b2 + hstep, voffB); PG8_STAGE(PG8_SA(0, 0), a2, voffA);
;             PG8_WAIT_V(8); PG8_WAIT_L(0); PG8_BAR; PG8_MMA(1, 0, At, B0); PG8_MMA(1, 1, At, B1); PG8_BAR; PG8_SCHED;
.LBB0_1591:
	s_add_u32 s14, s12, 0xfffc0080
	s_addc_u32 s15, s13, -1
	s_add_i32 s78, 0, 0x10000
	s_cmp_eq_u32 s88, 12
	s_cselect_b32 s29, s23, s15
	s_cselect_b32 s28, s75, s14
	v_add_u32_e32 v3, s78, v176
	s_cselect_b32 s15, s21, s80
	s_cselect_b32 s14, s76, s77
	s_add_i32 s89, 0, 0x14000
	ds_read_b128 v[134:137], v3
	ds_read_b128 v[138:141], v3 offset:1024
	ds_read_b128 v[168:171], v3 offset:2048
	ds_read_b128 v[172:175], v3 offset:3072
	v_add_u32_e32 v3, s89, v176
	ds_read_b128 v[180:183], v3
	ds_read_b128 v[184:187], v3 offset:1024
	ds_read_b128 v[188:191], v3 offset:2048
	ds_read_b128 v[212:215], v3 offset:3072
	v_lshl_add_u64 v[4:5], s[12:13], 0, v[164:165]
	s_add_i32 m0, s37, 0xc000
	ds_read_b128 v[216:219], v178
	ds_read_b128 v[220:223], v178 offset:1024
	ds_read_b128 v[224:227], v178 offset:2048
	ds_read_b128 v[228:231], v178 offset:3072
	ds_read_b128 v[232:235], v178 offset:4096
	ds_read_b128 v[236:239], v178 offset:5120
	ds_read_b128 v[240:243], v178 offset:6144
	ds_read_b128 v[244:247], v178 offset:7168
	global_load_lds_dwordx4 v[4:5], off
	v_lshl_add_u64 v[4:5], s[12:13], 0, v[166:167]
	s_add_i32 m0, s37, 0xe000
	s_nop 0
	global_load_lds_dwordx4 v[4:5], off
	s_waitcnt vmcnt(8)
	s_waitcnt lgkmcnt(0)
	s_barrier
	s_setprio 1
	s_waitcnt lgkmcnt(0)
	v_mfma_f32_16x16x32_bf16 v[130:133], v[134:137], v[216:219], v[130:133]
	v_mfma_f32_16x16x32_bf16 v[126:129], v[168:171], v[216:219], v[126:129]
	v_mfma_f32_16x16x32_bf16 v[122:125], v[134:137], v[224:227], v[122:125]
	v_mfma_f32_16x16x32_bf16 v[118:121], v[168:171], v[224:227], v[118:121]
	v_mfma_f32_16x16x32_bf16 v[114:117], v[134:137], v[232:235], v[114:117]
	v_mfma_f32_16x16x32_bf16 v[110:113], v[168:171], v[232:235], v[110:113]
	v_mfma_f32_16x16x32_bf16 v[106:109], v[134:137], v[240:243], v[106:109]
	v_mfma_f32_16x16x32_bf16 v[102:105], v[168:171], v[240:243], v[102:105]
	v_mfma_f32_16x16x32_bf16 v[130:133], v[138:141], v[220:223], v[130:133]
	v_mfma_f32_16x16x32_bf16 v[126:129], v[172:175], v[220:223], v[126:129]
	v_mfma_f32_16x16x32_bf16 v[122:125], v[138:141], v[228:231], v[122:125]
	v_mfma_f32_16x16x32_bf16 v[118:121], v[172:175], v[228:231], v[118:121]
	v_mfma_f32_16x16x32_bf16 v[114:117], v[138:141], v[236:239], v[114:117]
	v_mfma_f32_16x16x32_bf16 v[110:113], v[172:175], v[236:239], v[110:113]
	v_mfma_f32_16x16x32_bf16 v[106:109], v[138:141], v[244:247], v[106:109]
	v_mfma_f32_16x16x32_bf16 v[102:105], v[172:175], v[244:247], v[102:105]
	v_mfma_f32_16x16x32_bf16 v[98:101], v[180:183], v[216:219], v[98:101]
	v_mfma_f32_16x16x32_bf16 v[94:97], v[188:191], v[216:219], v[94:97]
	v_mfma_f32_16x16x32_bf16 v[90:93], v[180:183], v[224:227], v[90:93]
	v_mfma_f32_16x16x32_bf16 v[86:89], v[188:191], v[224:227], v[86:89]
	v_mfma_f32_16x16x32_bf16 v[82:85], v[180:183], v[232:235], v[82:85]
	v_mfma_f32_16x16x32_bf16 v[78:81], v[188:191], v[232:235], v[78:81]
	v_mfma_f32_16x16x32_bf16 v[74:77], v[180:183], v[240:243], v[74:77]
	v_mfma_f32_16x16x32_bf16 v[70:73], v[188:191], v[240:243], v[70:73]
	v_mfma_f32_16x16x32_bf16 v[98:101], v[184:187], v[220:223], v[98:101]
	v_mfma_f32_16x16x32_bf16 v[94:97], v[212:215], v[220:223], v[94:97]
	v_mfma_f32_16x16x32_bf16 v[90:93], v[184:187], v[228:231], v[90:93]
	v_mfma_f32_16x16x32_bf16 v[86:89], v[212:215], v[228:231], v[86:89]
	v_mfma_f32_16x16x32_bf16 v[82:85], v[184:187], v[236:239], v[82:85]
	v_mfma_f32_16x16x32_bf16 v[78:81], v[212:215], v[236:239], v[78:81]
	v_mfma_f32_16x16x32_bf16 v[74:77], v[184:187], v[244:247], v[74:77]
	v_mfma_f32_16x16x32_bf16 v[70:73], v[212:215], v[244:247], v[70:73]
	s_setprio 0
	s_barrier
	s_add_i32 s78, s78, s34
	v_lshl_add_u64 v[192:193], s[14:15], 0, v[160:161]
	s_mov_b32 m0, s78
	ds_read_b128 v[216:219], v178 offset:16384
	ds_read_b128 v[220:223], v178 offset:17408
	ds_read_b128 v[224:227], v178 offset:18432
	ds_read_b128 v[228:231], v178 offset:19456
	ds_read_b128 v[232:235], v178 offset:20480
	ds_read_b128 v[236:239], v178 offset:21504
	ds_read_b128 v[240:243], v178 offset:22528
	ds_read_b128 v[244:247], v178 offset:23552
	global_load_lds_dwordx4 v[192:193], off
	s_add_i32 m0, s78, 0x2000
	s_add_u32 s78, s14, 0x40000
	v_lshl_add_u64 v[248:249], s[14:15], 0, v[156:157]
	s_addc_u32 s79, s15, 0
	s_add_i32 s89, s89, s34
	global_load_lds_dwordx4 v[248:249], off
	v_lshl_add_u64 v[4:5], s[78:79], 0, v[160:161]
	s_mov_b32 m0, s89
	v_lshl_add_u64 v[250:251], s[28:29], 0, v[162:163]
	global_load_lds_dwordx4 v[4:5], off
	v_lshl_add_u64 v[4:5], s[78:79], 0, v[156:157]
	s_add_i32 m0, s89, 0x2000
	v_lshl_add_u64 v[198:199], s[28:29], 0, v[158:159]
	global_load_lds_dwordx4 v[4:5], off
	s_mov_b32 m0, s37
	s_nop 0
	global_load_lds_dwordx4 v[250:251], off
	s_mov_b32 m0, s38
	s_nop 0
	global_load_lds_dwordx4 v[198:199], off
	s_waitcnt vmcnt(8)
	s_waitcnt lgkmcnt(0)
	s_barrier
; #define PG8_STAGE(bufoff, gbase, voff) do { _Pragma("unroll") for (int _i = 0; _i < 2; ++_i) \
;         __builtin_amdgcn_global_load_lds((const unsigned*)((const char*)(gbase) + (voff)[_i]), (LAS unsigned*)(lds + (bufoff) + ldsw + _i * 8192), 16, 0, 0); } while (0)
; #define PG8_LDA(dst, b, h) do { _Pragma("unroll") for (int m = 0; m < 4; ++m) _Pragma("unroll") for (int k = 0; k < 2; ++k) dst[m][k] = *(const LAS bf16x8*)(lds + PG8_SA(b, h) + aoff + m * 2048 + k * 1024); } while (0)
; #define PG8_LDB(dst, b, h) do { _Pragma("unroll") for (int n = 0; n < 2; ++n) _Pragma("unroll") for (int k = 0; k < 2; ++k) dst[n][k] = *(const LAS bf16x8*)(lds + PG8_SB(b, h) + boff + n * 2048 + k * 1024); } while (0)
; #define PG8_MMA(ai, bj, At, Bt) do { __builtin_amdgcn_s_setprio(1); _Pragma("unroll") for (int m = 0; m < 4; ++m) _Pragma("unroll") for (int n = 0; n < 2; ++n) _Pragma("unroll") for (int k = 0; k < 2; ++k) \
;         acc[ai][bj][m][n] = __builtin_amdgcn_mfma_f32_16x16x32_bf16(Bt[n][k], At[m][k], acc[ai][bj][m][n], 0, 0, 0); __builtin_amdgcn_s_setprio(0); } while (0)
; #define PG8_WAIT_V(n) asm volatile("s_waitcnt vmcnt(" #n ")" ::: "memory")
; #define PG8_WAIT_L(n) asm volatile("s_waitcnt lgkmcnt(" #n ")" ::: "memory")
; #define PG8_BAR __builtin_amdgcn_s_barrier()
; #define PG8_SCHED __builtin_amdgcn_sched_barrier(0)
; template <class Epi>
; __device__ __forceinline__ void gemm_phase(LAS unsigned char* lds, const Gemm g, const StaticOrder& S, const Epi& E) {
;     ...
;             PG8_LDA(At, 0, 1); PG8_STAGE(PG8_SB(0, 0), b2, voffB); PG8_STAGE(PG8_SB(0, 1), b2 + hstep, voffB); PG8_STAGE(PG8_SA(0, 0), a2, voffA);
;             PG8_WAIT_V(8); PG8_WAIT_L(0); PG8_BAR; PG8_MMA(1, 0, At, B0); PG8_MMA(1, 1, At, B1); PG8_BAR; PG8_SCHED;
;             PG8_LDB(B0, 1, 0); PG8_LDB(B1, 1, 1); PG8_SCHED; PG8_LDA(At, 1, 0); PG8_STAGE(PG8_SA(0, 1), a2 + hstep, voffA);
;             PG8_WAIT_V(8); PG8_WAIT_L(0); PG8_BAR; PG8_MMA(0, 0, At, B0); PG8_MMA(0, 1, At, B1); PG8_BAR; PG8_SCHED;
	s_setprio 1
	s_waitcnt lgkmcnt(0)
	v_mfma_f32_16x16x32_bf16 v[66:69], v[134:137], v[216:219], v[66:69]
	v_mfma_f32_16x16x32_bf16 v[62:65], v[168:171], v[216:219], v[62:65]
	v_mfma_f32_16x16x32_bf16 v[58:61], v[134:137], v[224:227], v[58:61]
	v_mfma_f32_16x16x32_bf16 v[54:57], v[168:171], v[224:227], v[54:57]
	v_mfma_f32_16x16x32_bf16 v[50:53], v[134:137], v[232:235], v[50:53]
	v_mfma_f32_16x16x32_bf16 v[46:49], v[168:171], v[232:235], v[46:49]
	v_mfma_f32_16x16x32_bf16 v[42:45], v[134:137], v[240:243], v[42:45]
	v_mfma_f32_16x16x32_bf16 v[38:41], v[168:171], v[240:243], v[38:41]
	v_mfma_f32_16x16x32_bf16 v[66:69], v[138:141], v[220:223], v[66:69]
	v_mfma_f32_16x16x32_bf16 v[62:65], v[172:175], v[220:223], v[62:65]
	v_mfma_f32_16x16x32_bf16 v[58:61], v[138:141], v[228:231], v[58:61]
	v_mfma_f32_16x16x32_bf16 v[54:57], v[172:175], v[228:231], v[54:57]
	v_mfma_f32_16x16x32_bf16 v[50:53], v[138:141], v[236:239], v[50:53]
	v_mfma_f32_16x16x32_bf16 v[46:49], v[172:175], v[236:239], v[46:49]
	v_mfma_f32_16x16x32_bf16 v[42:45], v[138:141], v[244:247], v[42:45]
	v_mfma_f32_16x16x32_bf16 v[38:41], v[172:175], v[244:247], v[38:41]
	v_mfma_f32_16x16x32_bf16 v[34:37], v[180:183], v[216:219], v[34:37]
	v_mfma_f32_16x16x32_bf16 v[30:33], v[188:191], v[216:219], v[30:33]
	v_mfma_f32_16x16x32_bf16 v[26:29], v[180:183], v[224:227], v[26:29]
	v_mfma_f32_16x16x32_bf16 v[22:25], v[188:191], v[224:227], v[22:25]
	v_mfma_f32_16x16x32_bf16 v[18:21], v[180:183], v[232:235], v[18:21]
	v_mfma_f32_16x16x32_bf16 v[14:17], v[188:191], v[232:235], v[14:17]
	v_mfma_f32_16x16x32_bf16 v[10:13], v[180:183], v[240:243], v[10:13]
	v_mfma_f32_16x16x32_bf16 v[4:7], v[188:191], v[240:243], v[6:9]
	v_mfma_f32_16x16x32_bf16 v[34:37], v[184:187], v[220:223], v[34:37]
	v_mfma_f32_16x16x32_bf16 v[30:33], v[212:215], v[220:223], v[30:33]
	v_mfma_f32_16x16x32_bf16 v[26:29], v[184:187], v[228:231], v[26:29]
	v_mfma_f32_16x16x32_bf16 v[22:25], v[212:215], v[228:231], v[22:25]
	v_mfma_f32_16x16x32_bf16 v[18:21], v[184:187], v[236:239], v[18:21]
	v_mfma_f32_16x16x32_bf16 v[14:17], v[212:215], v[236:239], v[14:17]
	v_mfma_f32_16x16x32_bf16 v[10:13], v[184:187], v[244:247], v[10:13]
	v_mfma_f32_16x16x32_bf16 v[4:7], v[212:215], v[244:247], v[4:7]
	s_setprio 0
	s_barrier
	s_add_i32 s78, 0, 0x18000
	v_add_u32_e32 v3, s78, v176
	s_add_i32 s79, 0, 0x1c000
	ds_read_b128 v[134:137], v3
	ds_read_b128 v[138:141], v3 offset:1024
	ds_read_b128 v[168:171], v3 offset:2048
	ds_read_b128 v[172:175], v3 offset:3072
	v_add_u32_e32 v3, s79, v176
	ds_read_b128 v[180:183], v3
	ds_read_b128 v[184:187], v3 offset:1024
	ds_read_b128 v[188:191], v3 offset:2048
	ds_read_b128 v[212:215], v3 offset:3072
	s_add_u32 s28, s28, 0x40000
	s_addc_u32 s29, s29, 0
	s_mov_b32 m0, s39
	v_lshl_add_u64 v[8:9], s[28:29], 0, v[162:163]
	ds_read_b128 v[216:219], v178 offset:32768
	ds_read_b128 v[220:223], v178 offset:33792
	ds_read_b128 v[224:227], v178 offset:34816
	ds_read_b128 v[228:231], v178 offset:35840
	ds_read_b128 v[232:235], v178 offset:36864
	ds_read_b128 v[236:239], v178 offset:37888
	ds_read_b128 v[240:243], v178 offset:38912
	ds_read_b128 v[244:247], v178 offset:39936
	global_load_lds_dwordx4 v[8:9], off
	v_lshl_add_u64 v[8:9], s[28:29], 0, v[158:159]
	s_mov_b32 m0, s40
	s_nop 0
	global_load_lds_dwordx4 v[8:9], off
	s_waitcnt vmcnt(8)
	s_waitcnt lgkmcnt(0)
	s_barrier
	s_setprio 1
	s_waitcnt lgkmcnt(0)
	v_mfma_f32_16x16x32_bf16 v[130:133], v[134:137], v[216:219], v[130:133]
	v_mfma_f32_16x16x32_bf16 v[126:129], v[168:171], v[216:219], v[126:129]
	v_mfma_f32_16x16x32_bf16 v[122:125], v[134:137], v[224:227], v[122:125]
	v_mfma_f32_16x16x32_bf16 v[118:121], v[168:171], v[224:227], v[118:121]
	v_mfma_f32_16x16x32_bf16 v[114:117], v[134:137], v[232:235], v[114:117]
	v_mfma_f32_16x16x32_bf16 v[110:113], v[168:171], v[232:235], v[110:113]
	v_mfma_f32_16x16x32_bf16 v[106:109], v[134:137], v[240:243], v[106:109]
	v_mfma_f32_16x16x32_bf16 v[102:105], v[168:171], v[240:243], v[102:105]
	v_mfma_f32_16x16x32_bf16 v[130:133], v[138:141], v[220:223], v[130:133]
	v_mfma_f32_16x16x32_bf16 v[126:129], v[172:175], v[220:223], v[126:129]
	v_mfma_f32_16x16x32_bf16 v[122:125], v[138:141], v[228:231], v[122:125]
	v_mfma_f32_16x16x32_bf16 v[118:121], v[172:175], v[228:231], v[118:121]
	v_mfma_f32_16x16x32_bf16 v[114:117], v[138:141], v[236:239], v[114:117]
	v_mfma_f32_16x16x32_bf16 v[110:113], v[172:175], v[236:239], v[110:113]
	v_mfma_f32_16x16x32_bf16 v[106:109], v[138:141], v[244:247], v[106:109]
	v_mfma_f32_16x16x32_bf16 v[102:105], v[172:175], v[244:247], v[102:105]
	v_mfma_f32_16x16x32_bf16 v[98:101], v[180:183], v[216:219], v[98:101]
	v_mfma_f32_16x16x32_bf16 v[94:97], v[188:191], v[216:219], v[94:97]
	v_mfma_f32_16x16x32_bf16 v[90:93], v[180:183], v[224:227], v[90:93]
	v_mfma_f32_16x16x32_bf16 v[86:89], v[188:191], v[224:227], v[86:89]
	v_mfma_f32_16x16x32_bf16 v[82:85], v[180:183], v[232:235], v[82:85]
	v_mfma_f32_16x16x32_bf16 v[78:81], v[188:191], v[232:235], v[78:81]
	v_mfma_f32_16x16x32_bf16 v[74:77], v[180:183], v[240:243], v[74:77]
	v_mfma_f32_16x16x32_bf16 v[70:73], v[188:191], v[240:243], v[70:73]
	v_mfma_f32_16x16x32_bf16 v[98:101], v[184:187], v[220:223], v[98:101]
	v_mfma_f32_16x16x32_bf16 v[94:97], v[212:215], v[220:223], v[94:97]
	v_mfma_f32_16x16x32_bf16 v[90:93], v[184:187], v[228:231], v[90:93]
	v_mfma_f32_16x16x32_bf16 v[86:89], v[212:215], v[228:231], v[86:89]
	v_mfma_f32_16x16x32_bf16 v[82:85], v[184:187], v[236:239], v[82:85]
	v_mfma_f32_16x16x32_bf16 v[78:81], v[212:215], v[236:239], v[78:81]
	v_mfma_f32_16x16x32_bf16 v[74:77], v[184:187], v[244:247], v[74:77]
	v_mfma_f32_16x16x32_bf16 v[70:73], v[212:215], v[244:247], v[70:73]
	s_setprio 0
	s_barrier
; #define PG8_STAGE(bufoff, gbase, voff) do { _Pragma("unroll") for (int _i = 0; _i < 2; ++_i) \
;         __builtin_amdgcn_global_load_lds((const unsigned*)((const char*)(gbase) + (voff)[_i]), (LAS unsigned*)(lds + (bufoff) + ldsw + _i * 8192), 16, 0, 0); } while (0)
; #define PG8_LDA(dst, b, h) do { _Pragma("unroll") for (int m = 0; m < 4; ++m) _Pragma("unroll") for (int k = 0; k < 2; ++k) dst[m][k] = *(const LAS bf16x8*)(lds + PG8_SA(b, h) + aoff + m * 2048 + k * 1024); } while (0)
; #define PG8_MMA(ai, bj, At, Bt) do { __builtin_amdgcn_s_setprio(1); _Pragma("unroll") for (int m = 0; m < 4; ++m) _Pragma("unroll") for (int n = 0; n < 2; ++n) _Pragma("unroll") for (int k = 0; k < 2; ++k) \
;         acc[ai][bj][m][n] = __builtin_amdgcn_mfma_f32_16x16x32_bf16(Bt[n][k], At[m][k], acc[ai][bj][m][n], 0, 0, 0); __builtin_amdgcn_s_setprio(0); } while (0)
; #define PG8_WAIT_V(n) asm volatile("s_waitcnt vmcnt(" #n ")" ::: "memory")
; #define PG8_WAIT_L(n) asm volatile("s_waitcnt lgkmcnt(" #n ")" ::: "memory")
; #define PG8_BAR __builtin_amdgcn_s_barrier()
; #define PG8_SCHED __builtin_amdgcn_sched_barrier(0)
; template <class Epi>
; __device__ __forceinline__ void gemm_phase(LAS unsigned char* lds, const Gemm g, const StaticOrder& S, const Epi& E) {
;     ...
;             PG8_LDA(At, 1, 1); PG8_STAGE(PG8_SB(1, 0), b3, voffB); PG8_STAGE(PG8_SB(1, 1), b3 + hstep, voffB); PG8_STAGE(PG8_SA(1, 0), a3, voffA);
;             PG8_WAIT_V(8); PG8_WAIT_L(0); PG8_BAR; PG8_MMA(1, 0, At, B0); PG8_MMA(1, 1, At, B1); PG8_BAR; PG8_SCHED;
;         }
;         if (wr == 0) PG8_BAR;
	s_add_i32 s28, s78, s34
	v_lshl_add_u64 v[8:9], v[192:193], 0, s[68:69]
	s_mov_b32 m0, s28
	ds_read_b128 v[216:219], v178 offset:49152
	ds_read_b128 v[220:223], v178 offset:50176
	ds_read_b128 v[224:227], v178 offset:51200
	ds_read_b128 v[228:231], v178 offset:52224
	ds_read_b128 v[232:235], v178 offset:53248
	ds_read_b128 v[236:239], v178 offset:54272
	ds_read_b128 v[240:243], v178 offset:55296
	ds_read_b128 v[244:247], v178 offset:56320
	global_load_lds_dwordx4 v[8:9], off
	s_add_i32 m0, s28, 0x2000
	s_add_u32 s14, s14, 0x40080
	v_lshl_add_u64 v[8:9], v[248:249], 0, s[68:69]
	s_addc_u32 s15, s15, 0
	s_add_i32 s28, s79, s34
	global_load_lds_dwordx4 v[8:9], off
	v_lshl_add_u64 v[8:9], s[14:15], 0, v[160:161]
	s_mov_b32 m0, s28
	s_nop 0
	global_load_lds_dwordx4 v[8:9], off
	v_lshl_add_u64 v[8:9], s[14:15], 0, v[156:157]
	s_add_i32 m0, s28, 0x2000
	s_nop 0
	global_load_lds_dwordx4 v[8:9], off
	v_lshl_add_u64 v[8:9], v[250:251], 0, s[68:69]
	s_mov_b32 m0, s41
	s_nop 0
	global_load_lds_dwordx4 v[8:9], off
	v_lshl_add_u64 v[8:9], v[198:199], 0, s[68:69]
	s_mov_b32 m0, s44
	s_nop 0
	global_load_lds_dwordx4 v[8:9], off
	s_waitcnt vmcnt(8)
	s_waitcnt lgkmcnt(0)
	s_barrier
	s_setprio 1
	s_waitcnt lgkmcnt(0)
	v_mfma_f32_16x16x32_bf16 v[66:69], v[134:137], v[216:219], v[66:69]
	v_mfma_f32_16x16x32_bf16 v[62:65], v[168:171], v[216:219], v[62:65]
	v_mfma_f32_16x16x32_bf16 v[58:61], v[134:137], v[224:227], v[58:61]
	v_mfma_f32_16x16x32_bf16 v[54:57], v[168:171], v[224:227], v[54:57]
	v_mfma_f32_16x16x32_bf16 v[50:53], v[134:137], v[232:235], v[50:53]
	v_mfma_f32_16x16x32_bf16 v[46:49], v[168:171], v[232:235], v[46:49]
	v_mfma_f32_16x16x32_bf16 v[42:45], v[134:137], v[240:243], v[42:45]
	v_mfma_f32_16x16x32_bf16 v[38:41], v[168:171], v[240:243], v[38:41]
	v_mfma_f32_16x16x32_bf16 v[66:69], v[138:141], v[220:223], v[66:69]
	v_mfma_f32_16x16x32_bf16 v[62:65], v[172:175], v[220:223], v[62:65]
	v_mfma_f32_16x16x32_bf16 v[58:61], v[138:141], v[228:231], v[58:61]
	v_mfma_f32_16x16x32_bf16 v[54:57], v[172:175], v[228:231], v[54:57]
	v_mfma_f32_16x16x32_bf16 v[50:53], v[138:141], v[236:239], v[50:53]
	v_mfma_f32_16x16x32_bf16 v[46:49], v[172:175], v[236:239], v[46:49]
	v_mfma_f32_16x16x32_bf16 v[42:45], v[138:141], v[244:247], v[42:45]
	v_mfma_f32_16x16x32_bf16 v[38:41], v[172:175], v[244:247], v[38:41]
	v_mfma_f32_16x16x32_bf16 v[34:37], v[180:183], v[216:219], v[34:37]
	v_mfma_f32_16x16x32_bf16 v[30:33], v[188:191], v[216:219], v[30:33]
	v_mfma_f32_16x16x32_bf16 v[26:29], v[180:183], v[224:227], v[26:29]
	v_mfma_f32_16x16x32_bf16 v[22:25], v[188:191], v[224:227], v[22:25]
	v_mfma_f32_16x16x32_bf16 v[18:21], v[180:183], v[232:235], v[18:21]
	v_mfma_f32_16x16x32_bf16 v[14:17], v[188:191], v[232:235], v[14:17]
	v_mfma_f32_16x16x32_bf16 v[8:11], v[180:183], v[240:243], v[10:13]
	v_mfma_f32_16x16x32_bf16 v[4:7], v[188:191], v[240:243], v[4:7]
	v_mfma_f32_16x16x32_bf16 v[34:37], v[184:187], v[220:223], v[34:37]
	v_mfma_f32_16x16x32_bf16 v[30:33], v[212:215], v[220:223], v[30:33]
	v_mfma_f32_16x16x32_bf16 v[26:29], v[184:187], v[228:231], v[26:29]
	v_mfma_f32_16x16x32_bf16 v[22:25], v[212:215], v[228:231], v[22:25]
	v_mfma_f32_16x16x32_bf16 v[18:21], v[184:187], v[236:239], v[18:21]
	v_mfma_f32_16x16x32_bf16 v[14:17], v[212:215], v[236:239], v[14:17]
	v_mfma_f32_16x16x32_bf16 v[10:13], v[184:187], v[244:247], v[8:11]
	v_mfma_f32_16x16x32_bf16 v[6:9], v[212:215], v[244:247], v[4:7]
	s_setprio 0
	s_barrier
	s_add_i32 s88, s88, 2
	s_add_u32 s12, s12, 0x100
	s_addc_u32 s13, s13, 0
	s_add_u32 s77, s77, 0x100
	s_addc_u32 s80, s80, 0
	s_cmp_gt_u32 s88, 13
	s_cbranch_scc0 .LBB0_1591
	s_and_b64 vcc, exec, s[18:19]
	s_cbranch_vccz .LBB0_1594
	s_barrier

; #define PG8_STAGE(bufoff, gbase, voff) do { _Pragma("unroll") for (int _i = 0; _i < 2; ++_i) \
;         __builtin_amdgcn_global_load_lds((const unsigned*)((const char*)(gbase) + (voff)[_i]), (LAS unsigned*)(lds + (bufoff) + ldsw + _i * 8192), 16, 0, 0); } while (0)
; #define PG8_LDA(dst, b, h) do { _Pragma("unroll") for (int m = 0; m < 4; ++m) _Pragma("unroll") for (int k = 0; k < 2; ++k) dst[m][k] = *(const LAS bf16x8*)(lds + PG8_SA(b, h) + aoff + m * 2048 + k * 1024); } while (0)
; #define PG8_LDB(dst, b, h) do { _Pragma("unroll") for (int n = 0; n < 2; ++n) _Pragma("unroll") for (int k = 0; k < 2; ++k) dst[n][k] = *(const LAS bf16x8*)(lds + PG8_SB(b, h) + boff + n * 2048 + k * 1024); } while (0)
; #define PG8_MMA(ai, bj, At, Bt) do { __builtin_amdgcn_s_setprio(1); _Pragma("unroll") for (int m = 0; m < 4; ++m) _Pragma("unroll") for (int n = 0; n < 2; ++n) _Pragma("unroll") for (int k = 0; k < 2; ++k) \
;         acc[ai][bj][m][n] = __builtin_amdgcn_mfma_f32_16x16x32_bf16(Bt[n][k], At[m][k], acc[ai][bj][m][n], 0, 0, 0); __builtin_amdgcn_s_setprio(0); } while (0)
; #define PG8_WAIT_V(n) asm volatile("s_waitcnt vmcnt(" #n ")" ::: "memory")
; #define PG8_WAIT_L(n) asm volatile("s_waitcnt lgkmcnt(" #n ")" ::: "memory")
; #define PG8_BAR __builtin_amdgcn_s_barrier()
; #define PG8_SCHED __builtin_amdgcn_sched_barrier(0)
; template <class Epi>
; __device__ __forceinline__ void gemm_phase(LAS unsigned char* lds, const Gemm g, const StaticOrder& S, const Epi& E) {
;     ...
;         for (int t = 0; t < nt; t += 2) {
;             const bool last = (t == nt - 2);
;             const char* a1 = cA + (size_t)(t + 1) * kstep;
;             const char* a2 = last ? nA : cA + (size_t)(t + 2) * kstep; const char* b2 = last ? nB : cB + (size_t)(t + 2) * kstep;
;             const char* a3 = a2 + kstep; const char* b3 = b2 + kstep;
;             PG8_LDB(B0, 0, 0); PG8_LDB(B1, 0, 1); PG8_SCHED; PG8_LDA(At, 0, 0); PG8_STAGE(PG8_SA(1, 1), a1 + hstep, voffA);
;             PG8_WAIT_V(8); PG8_WAIT_L(0); PG8_BAR; PG8_MMA(0, 0, At, B0); PG8_MMA(0, 1, At, B1); PG8_BAR; PG8_SCHED;
;             PG8_LDA(At, 0, 1); PG8_STAGE(PG8_SB(0, 0), b2, voffB); PG8_STAGE(PG8_SB(0, 1), b2 + hstep, voffB); PG8_STAGE(PG8_SA(0, 0), a2, voffA);
;             PG8_WAIT_V(8); PG8_WAIT_L(0); PG8_BAR; PG8_MMA(1, 0, At, B0); PG8_MMA(1, 1, At, B1); PG8_BAR; PG8_SCHED;
.LBB0_1741:
	s_add_u32 s28, s26, 0xfff80080
	s_addc_u32 s29, s27, -1
	s_add_i32 s78, 0, 0x10000
	s_cmp_eq_u32 s80, 28
	s_cselect_b32 s31, s21, s29
	s_cselect_b32 s30, s74, s28
	v_add_u32_e32 v162, s78, v147
	s_cselect_b32 s29, s19, s77
	s_cselect_b32 s28, s75, s76
	s_add_i32 s88, 0, 0x14000
	ds_read_b128 v[158:161], v162
	ds_read_b128 v[166:169], v162 offset:1024
	ds_read_b128 v[170:173], v162 offset:2048
	ds_read_b128 v[174:177], v162 offset:3072
	v_add_u32_e32 v162, s88, v147
	ds_read_b128 v[178:181], v162
	ds_read_b128 v[182:185], v162 offset:1024
	ds_read_b128 v[186:189], v162 offset:2048
	ds_read_b128 v[190:193], v162 offset:3072
	v_lshl_add_u64 v[162:163], s[26:27], 0, v[140:141]
	s_add_i32 m0, s35, 0xc000
	ds_read_b128 v[212:215], v165
	ds_read_b128 v[216:219], v165 offset:1024
	ds_read_b128 v[220:223], v165 offset:2048
	ds_read_b128 v[224:227], v165 offset:3072
	ds_read_b128 v[228:231], v165 offset:4096
	ds_read_b128 v[232:235], v165 offset:5120
	ds_read_b128 v[236:239], v165 offset:6144
	ds_read_b128 v[240:243], v165 offset:7168
	global_load_lds_dwordx4 v[162:163], off
	v_lshl_add_u64 v[162:163], s[26:27], 0, v[156:157]
	s_add_i32 m0, s35, 0xe000
	s_nop 0
	global_load_lds_dwordx4 v[162:163], off
	s_waitcnt vmcnt(8)
	s_waitcnt lgkmcnt(0)
	s_barrier
	s_setprio 1
	s_waitcnt lgkmcnt(0)
	v_mfma_f32_16x16x32_bf16 v[128:131], v[158:161], v[212:215], v[128:131]
	v_mfma_f32_16x16x32_bf16 v[124:127], v[170:173], v[212:215], v[124:127]
	v_mfma_f32_16x16x32_bf16 v[112:115], v[158:161], v[220:223], v[112:115]
	v_mfma_f32_16x16x32_bf16 v[108:111], v[170:173], v[220:223], v[108:111]
	v_mfma_f32_16x16x32_bf16 v[96:99], v[158:161], v[228:231], v[96:99]
	v_mfma_f32_16x16x32_bf16 v[92:95], v[170:173], v[228:231], v[92:95]
	v_mfma_f32_16x16x32_bf16 v[80:83], v[158:161], v[236:239], v[80:83]
	v_mfma_f32_16x16x32_bf16 v[76:79], v[170:173], v[236:239], v[76:79]
	v_mfma_f32_16x16x32_bf16 v[128:131], v[166:169], v[216:219], v[128:131]
	v_mfma_f32_16x16x32_bf16 v[124:127], v[174:177], v[216:219], v[124:127]
	v_mfma_f32_16x16x32_bf16 v[112:115], v[166:169], v[224:227], v[112:115]
	v_mfma_f32_16x16x32_bf16 v[108:111], v[174:177], v[224:227], v[108:111]
	v_mfma_f32_16x16x32_bf16 v[96:99], v[166:169], v[232:235], v[96:99]
	v_mfma_f32_16x16x32_bf16 v[92:95], v[174:177], v[232:235], v[92:95]
	v_mfma_f32_16x16x32_bf16 v[80:83], v[166:169], v[240:243], v[80:83]
	v_mfma_f32_16x16x32_bf16 v[76:79], v[174:177], v[240:243], v[76:79]
	v_mfma_f32_16x16x32_bf16 v[120:123], v[178:181], v[212:215], v[120:123]
	v_mfma_f32_16x16x32_bf16 v[116:119], v[186:189], v[212:215], v[116:119]
	v_mfma_f32_16x16x32_bf16 v[104:107], v[178:181], v[220:223], v[104:107]
	v_mfma_f32_16x16x32_bf16 v[100:103], v[186:189], v[220:223], v[100:103]
	v_mfma_f32_16x16x32_bf16 v[88:91], v[178:181], v[228:231], v[88:91]
	v_mfma_f32_16x16x32_bf16 v[84:87], v[186:189], v[228:231], v[84:87]
	v_mfma_f32_16x16x32_bf16 v[72:75], v[178:181], v[236:239], v[72:75]
	v_mfma_f32_16x16x32_bf16 v[68:71], v[186:189], v[236:239], v[68:71]
	v_mfma_f32_16x16x32_bf16 v[120:123], v[182:185], v[216:219], v[120:123]
	v_mfma_f32_16x16x32_bf16 v[116:119], v[190:193], v[216:219], v[116:119]
	v_mfma_f32_16x16x32_bf16 v[104:107], v[182:185], v[224:227], v[104:107]
	v_mfma_f32_16x16x32_bf16 v[100:103], v[190:193], v[224:227], v[100:103]
	v_mfma_f32_16x16x32_bf16 v[88:91], v[182:185], v[232:235], v[88:91]
	v_mfma_f32_16x16x32_bf16 v[84:87], v[190:193], v[232:235], v[84:87]
	v_mfma_f32_16x16x32_bf16 v[72:75], v[182:185], v[240:243], v[72:75]
	v_mfma_f32_16x16x32_bf16 v[68:71], v[190:193], v[240:243], v[68:71]
	s_setprio 0
	s_barrier
	s_add_i32 s78, s78, s34
	v_lshl_add_u64 v[162:163], s[28:29], 0, v[136:137]
	s_mov_b32 m0, s78
	ds_read_b128 v[212:215], v165 offset:16384
	ds_read_b128 v[216:219], v165 offset:17408
	ds_read_b128 v[220:223], v165 offset:18432
	ds_read_b128 v[224:227], v165 offset:19456
	ds_read_b128 v[228:231], v165 offset:20480
	ds_read_b128 v[232:235], v165 offset:21504
	ds_read_b128 v[236:239], v165 offset:22528
	ds_read_b128 v[240:243], v165 offset:23552
	global_load_lds_dwordx4 v[162:163], off
	s_add_i32 m0, s78, 0x2000
	s_add_u32 s78, s28, 0x80000
	v_lshl_add_u64 v[198:199], s[28:29], 0, v[132:133]
	s_addc_u32 s79, s29, 0
	s_add_i32 s88, s88, s34
	global_load_lds_dwordx4 v[198:199], off
	v_lshl_add_u64 v[244:245], s[78:79], 0, v[136:137]
	s_mov_b32 m0, s88
	v_lshl_add_u64 v[246:247], s[30:31], 0, v[134:135]
	global_load_lds_dwordx4 v[244:245], off
	v_lshl_add_u64 v[244:245], s[78:79], 0, v[132:133]
	s_add_i32 m0, s88, 0x2000
	s_nop 0
	global_load_lds_dwordx4 v[244:245], off
	v_lshl_add_u64 v[244:245], s[30:31], 0, v[138:139]
	s_mov_b32 m0, s35
	s_nop 0
	global_load_lds_dwordx4 v[244:245], off
	s_mov_b32 m0, s36
	s_nop 0
	global_load_lds_dwordx4 v[246:247], off
	s_waitcnt vmcnt(8)
	s_waitcnt lgkmcnt(0)
	s_barrier
; #define PG8_STAGE(bufoff, gbase, voff) do { _Pragma("unroll") for (int _i = 0; _i < 2; ++_i) \
;         __builtin_amdgcn_global_load_lds((const unsigned*)((const char*)(gbase) + (voff)[_i]), (LAS unsigned*)(lds + (bufoff) + ldsw + _i * 8192), 16, 0, 0); } while (0)
; #define PG8_LDA(dst, b, h) do { _Pragma("unroll") for (int m = 0; m < 4; ++m) _Pragma("unroll") for (int k = 0; k < 2; ++k) dst[m][k] = *(const LAS bf16x8*)(lds + PG8_SA(b, h) + aoff + m * 2048 + k * 1024); } while (0)
; #define PG8_LDB(dst, b, h) do { _Pragma("unroll") for (int n = 0; n < 2; ++n) _Pragma("unroll") for (int k = 0; k < 2; ++k) dst[n][k] = *(const LAS bf16x8*)(lds + PG8_SB(b, h) + boff + n * 2048 + k * 1024); } while (0)
; #define PG8_MMA(ai, bj, At, Bt) do { __builtin_amdgcn_s_setprio(1); _Pragma("unroll") for (int m = 0; m < 4; ++m) _Pragma("unroll") for (int n = 0; n < 2; ++n) _Pragma("unroll") for (int k = 0; k < 2; ++k) \
;         acc[ai][bj][m][n] = __builtin_amdgcn_mfma_f32_16x16x32_bf16(Bt[n][k], At[m][k], acc[ai][bj][m][n], 0, 0, 0); __builtin_amdgcn_s_setprio(0); } while (0)
; #define PG8_WAIT_V(n) asm volatile("s_waitcnt vmcnt(" #n ")" ::: "memory")
; #define PG8_WAIT_L(n) asm volatile("s_waitcnt lgkmcnt(" #n ")" ::: "memory")
; #define PG8_BAR __builtin_amdgcn_s_barrier()
; #define PG8_SCHED __builtin_amdgcn_sched_barrier(0)
; template <class Epi>
; __device__ __forceinline__ void gemm_phase(LAS unsigned char* lds, const Gemm g, const StaticOrder& S, const Epi& E) {
;     ...
;             PG8_LDA(At, 0, 1); PG8_STAGE(PG8_SB(0, 0), b2, voffB); PG8_STAGE(PG8_SB(0, 1), b2 + hstep, voffB); PG8_STAGE(PG8_SA(0, 0), a2, voffA);
;             PG8_WAIT_V(8); PG8_WAIT_L(0); PG8_BAR; PG8_MMA(1, 0, At, B0); PG8_MMA(1, 1, At, B1); PG8_BAR; PG8_SCHED;
;             PG8_LDB(B0, 1, 0); PG8_LDB(B1, 1, 1); PG8_SCHED; PG8_LDA(At, 1, 0); PG8_STAGE(PG8_SA(0, 1), a2 + hstep, voffA);
;             PG8_WAIT_V(8); PG8_WAIT_L(0); PG8_BAR; PG8_MMA(0, 0, At, B0); PG8_MMA(0, 1, At, B1); PG8_BAR; PG8_SCHED;
	s_setprio 1
	s_waitcnt lgkmcnt(0)
	v_mfma_f32_16x16x32_bf16 v[64:67], v[158:161], v[212:215], v[64:67]
	v_mfma_f32_16x16x32_bf16 v[60:63], v[170:173], v[212:215], v[60:63]
	v_mfma_f32_16x16x32_bf16 v[48:51], v[158:161], v[220:223], v[48:51]
	v_mfma_f32_16x16x32_bf16 v[44:47], v[170:173], v[220:223], v[44:47]
	v_mfma_f32_16x16x32_bf16 v[32:35], v[158:161], v[228:231], v[32:35]
	v_mfma_f32_16x16x32_bf16 v[28:31], v[170:173], v[228:231], v[28:31]
	v_mfma_f32_16x16x32_bf16 v[16:19], v[158:161], v[236:239], v[16:19]
	v_mfma_f32_16x16x32_bf16 v[12:15], v[170:173], v[236:239], v[12:15]
	v_mfma_f32_16x16x32_bf16 v[64:67], v[166:169], v[216:219], v[64:67]
	v_mfma_f32_16x16x32_bf16 v[60:63], v[174:177], v[216:219], v[60:63]
	v_mfma_f32_16x16x32_bf16 v[48:51], v[166:169], v[224:227], v[48:51]
	v_mfma_f32_16x16x32_bf16 v[44:47], v[174:177], v[224:227], v[44:47]
	v_mfma_f32_16x16x32_bf16 v[32:35], v[166:169], v[232:235], v[32:35]
	v_mfma_f32_16x16x32_bf16 v[28:31], v[174:177], v[232:235], v[28:31]
	v_mfma_f32_16x16x32_bf16 v[16:19], v[166:169], v[240:243], v[16:19]
	v_mfma_f32_16x16x32_bf16 v[12:15], v[174:177], v[240:243], v[12:15]
	v_mfma_f32_16x16x32_bf16 v[56:59], v[178:181], v[212:215], v[56:59]
	v_mfma_f32_16x16x32_bf16 v[52:55], v[186:189], v[212:215], v[52:55]
	v_mfma_f32_16x16x32_bf16 v[40:43], v[178:181], v[220:223], v[40:43]
	v_mfma_f32_16x16x32_bf16 v[36:39], v[186:189], v[220:223], v[36:39]
	v_mfma_f32_16x16x32_bf16 v[24:27], v[178:181], v[228:231], v[24:27]
	v_mfma_f32_16x16x32_bf16 v[20:23], v[186:189], v[228:231], v[20:23]
	v_mfma_f32_16x16x32_bf16 v[8:11], v[178:181], v[236:239], v[8:11]
	v_mfma_f32_16x16x32_bf16 v[4:7], v[186:189], v[236:239], v[4:7]
	v_mfma_f32_16x16x32_bf16 v[56:59], v[182:185], v[216:219], v[56:59]
	v_mfma_f32_16x16x32_bf16 v[52:55], v[190:193], v[216:219], v[52:55]
	v_mfma_f32_16x16x32_bf16 v[40:43], v[182:185], v[224:227], v[40:43]
	v_mfma_f32_16x16x32_bf16 v[36:39], v[190:193], v[224:227], v[36:39]
	v_mfma_f32_16x16x32_bf16 v[24:27], v[182:185], v[232:235], v[24:27]
	v_mfma_f32_16x16x32_bf16 v[20:23], v[190:193], v[232:235], v[20:23]
	v_mfma_f32_16x16x32_bf16 v[8:11], v[182:185], v[240:243], v[8:11]
	v_mfma_f32_16x16x32_bf16 v[4:7], v[190:193], v[240:243], v[4:7]
	s_setprio 0
	s_barrier
	s_add_i32 s78, 0, 0x18000
	s_add_i32 s79, 0, 0x1c000
	v_add_u32_e32 v174, s78, v147
	v_add_u32_e32 v190, s79, v147
	ds_read_b128 v[158:161], v174
	ds_read_b128 v[166:169], v174 offset:1024
	ds_read_b128 v[170:173], v174 offset:2048
	ds_read_b128 v[174:177], v174 offset:3072
	ds_read_b128 v[178:181], v190
	ds_read_b128 v[182:185], v190 offset:1024
	ds_read_b128 v[186:189], v190 offset:2048
	ds_read_b128 v[190:193], v190 offset:3072
	s_add_u32 s30, s30, 0x80000
	s_addc_u32 s31, s31, 0
	s_mov_b32 m0, s37
	v_lshl_add_u64 v[248:249], s[30:31], 0, v[138:139]
	ds_read_b128 v[212:215], v165 offset:32768
	ds_read_b128 v[216:219], v165 offset:33792
	ds_read_b128 v[220:223], v165 offset:34816
	ds_read_b128 v[224:227], v165 offset:35840
	ds_read_b128 v[228:231], v165 offset:36864
	ds_read_b128 v[232:235], v165 offset:37888
	ds_read_b128 v[236:239], v165 offset:38912
	ds_read_b128 v[240:243], v165 offset:39936
	global_load_lds_dwordx4 v[248:249], off
	v_lshl_add_u64 v[248:249], s[30:31], 0, v[134:135]
	s_mov_b32 m0, s38
	s_nop 0
	global_load_lds_dwordx4 v[248:249], off
	s_waitcnt vmcnt(8)
	s_waitcnt lgkmcnt(0)
	s_barrier
	s_setprio 1
	s_waitcnt lgkmcnt(0)
	v_mfma_f32_16x16x32_bf16 v[128:131], v[158:161], v[212:215], v[128:131]
	v_mfma_f32_16x16x32_bf16 v[124:127], v[170:173], v[212:215], v[124:127]
	v_mfma_f32_16x16x32_bf16 v[112:115], v[158:161], v[220:223], v[112:115]
	v_mfma_f32_16x16x32_bf16 v[108:111], v[170:173], v[220:223], v[108:111]
	v_mfma_f32_16x16x32_bf16 v[96:99], v[158:161], v[228:231], v[96:99]
	v_mfma_f32_16x16x32_bf16 v[92:95], v[170:173], v[228:231], v[92:95]
	v_mfma_f32_16x16x32_bf16 v[80:83], v[158:161], v[236:239], v[80:83]
	v_mfma_f32_16x16x32_bf16 v[76:79], v[170:173], v[236:239], v[76:79]
	v_mfma_f32_16x16x32_bf16 v[128:131], v[166:169], v[216:219], v[128:131]
	v_mfma_f32_16x16x32_bf16 v[124:127], v[174:177], v[216:219], v[124:127]
	v_mfma_f32_16x16x32_bf16 v[112:115], v[166:169], v[224:227], v[112:115]
	v_mfma_f32_16x16x32_bf16 v[108:111], v[174:177], v[224:227], v[108:111]
	v_mfma_f32_16x16x32_bf16 v[96:99], v[166:169], v[232:235], v[96:99]
	v_mfma_f32_16x16x32_bf16 v[92:95], v[174:177], v[232:235], v[92:95]
	v_mfma_f32_16x16x32_bf16 v[80:83], v[166:169], v[240:243], v[80:83]
	v_mfma_f32_16x16x32_bf16 v[76:79], v[174:177], v[240:243], v[76:79]
	v_mfma_f32_16x16x32_bf16 v[120:123], v[178:181], v[212:215], v[120:123]
	v_mfma_f32_16x16x32_bf16 v[116:119], v[186:189], v[212:215], v[116:119]
	v_mfma_f32_16x16x32_bf16 v[104:107], v[178:181], v[220:223], v[104:107]
	v_mfma_f32_16x16x32_bf16 v[100:103], v[186:189], v[220:223], v[100:103]
	v_mfma_f32_16x16x32_bf16 v[88:91], v[178:181], v[228:231], v[88:91]
	v_mfma_f32_16x16x32_bf16 v[84:87], v[186:189], v[228:231], v[84:87]
	v_mfma_f32_16x16x32_bf16 v[72:75], v[178:181], v[236:239], v[72:75]
	v_mfma_f32_16x16x32_bf16 v[68:71], v[186:189], v[236:239], v[68:71]
	v_mfma_f32_16x16x32_bf16 v[120:123], v[182:185], v[216:219], v[120:123]
	v_mfma_f32_16x16x32_bf16 v[116:119], v[190:193], v[216:219], v[116:119]
	v_mfma_f32_16x16x32_bf16 v[104:107], v[182:185], v[224:227], v[104:107]
	v_mfma_f32_16x16x32_bf16 v[100:103], v[190:193], v[224:227], v[100:103]
	v_mfma_f32_16x16x32_bf16 v[88:91], v[182:185], v[232:235], v[88:91]
	v_mfma_f32_16x16x32_bf16 v[84:87], v[190:193], v[232:235], v[84:87]
	v_mfma_f32_16x16x32_bf16 v[72:75], v[182:185], v[240:243], v[72:75]
	v_mfma_f32_16x16x32_bf16 v[68:71], v[190:193], v[240:243], v[68:71]
	s_setprio 0
	s_barrier
; #define PG8_STAGE(bufoff, gbase, voff) do { _Pragma("unroll") for (int _i = 0; _i < 2; ++_i) \
;         __builtin_amdgcn_global_load_lds((const unsigned*)((const char*)(gbase) + (voff)[_i]), (LAS unsigned*)(lds + (bufoff) + ldsw + _i * 8192), 16, 0, 0); } while (0)
; #define PG8_LDA(dst, b, h) do { _Pragma("unroll") for (int m = 0; m < 4; ++m) _Pragma("unroll") for (int k = 0; k < 2; ++k) dst[m][k] = *(const LAS bf16x8*)(lds + PG8_SA(b, h) + aoff + m * 2048 + k * 1024); } while (0)
; #define PG8_MMA(ai, bj, At, Bt) do { __builtin_amdgcn_s_setprio(1); _Pragma("unroll") for (int m = 0; m < 4; ++m) _Pragma("unroll") for (int n = 0; n < 2; ++n) _Pragma("unroll") for (int k = 0; k < 2; ++k) \
;         acc[ai][bj][m][n] = __builtin_amdgcn_mfma_f32_16x16x32_bf16(Bt[n][k], At[m][k], acc[ai][bj][m][n], 0, 0, 0); __builtin_amdgcn_s_setprio(0); } while (0)
; #define PG8_WAIT_V(n) asm volatile("s_waitcnt vmcnt(" #n ")" ::: "memory")
; #define PG8_WAIT_L(n) asm volatile("s_waitcnt lgkmcnt(" #n ")" ::: "memory")
; #define PG8_BAR __builtin_amdgcn_s_barrier()
; #define PG8_SCHED __builtin_amdgcn_sched_barrier(0)
; template <class Epi>
; __device__ __forceinline__ void gemm_phase(LAS unsigned char* lds, const Gemm g, const StaticOrder& S, const Epi& E) {
;     ...
;             PG8_LDA(At, 1, 1); PG8_STAGE(PG8_SB(1, 0), b3, voffB); PG8_STAGE(PG8_SB(1, 1), b3 + hstep, voffB); PG8_STAGE(PG8_SA(1, 0), a3, voffA);
;             PG8_WAIT_V(8); PG8_WAIT_L(0); PG8_BAR; PG8_MMA(1, 0, At, B0); PG8_MMA(1, 1, At, B1); PG8_BAR; PG8_SCHED;
;         }
;         if (wr == 0) PG8_BAR;
	s_add_i32 s30, s78, s34
	v_lshl_add_u64 v[162:163], v[162:163], 0, s[68:69]
	s_mov_b32 m0, s30
	ds_read_b128 v[212:215], v165 offset:49152
	ds_read_b128 v[216:219], v165 offset:50176
	ds_read_b128 v[220:223], v165 offset:51200
	ds_read_b128 v[224:227], v165 offset:52224
	ds_read_b128 v[228:231], v165 offset:53248
	ds_read_b128 v[232:235], v165 offset:54272
	ds_read_b128 v[236:239], v165 offset:55296
	ds_read_b128 v[240:243], v165 offset:56320
	global_load_lds_dwordx4 v[162:163], off
	s_add_i32 m0, s30, 0x2000
	s_add_u32 s28, s28, 0x80080
	v_lshl_add_u64 v[162:163], v[198:199], 0, s[68:69]
	s_addc_u32 s29, s29, 0
	s_add_i32 s30, s79, s34
	global_load_lds_dwordx4 v[162:163], off
	v_lshl_add_u64 v[162:163], s[28:29], 0, v[136:137]
	s_mov_b32 m0, s30
	s_nop 0
	global_load_lds_dwordx4 v[162:163], off
	v_lshl_add_u64 v[162:163], s[28:29], 0, v[132:133]
	s_add_i32 m0, s30, 0x2000
	s_nop 0
	global_load_lds_dwordx4 v[162:163], off
	v_lshl_add_u64 v[162:163], v[244:245], 0, s[68:69]
	s_mov_b32 m0, s40
	s_nop 0
	global_load_lds_dwordx4 v[162:163], off
	v_lshl_add_u64 v[162:163], v[246:247], 0, s[68:69]
	s_mov_b32 m0, s41
	s_nop 0
	global_load_lds_dwordx4 v[162:163], off
	s_waitcnt vmcnt(8)
	s_waitcnt lgkmcnt(0)
	s_barrier
	s_setprio 1
	s_waitcnt lgkmcnt(0)
	v_mfma_f32_16x16x32_bf16 v[64:67], v[158:161], v[212:215], v[64:67]
	v_mfma_f32_16x16x32_bf16 v[60:63], v[170:173], v[212:215], v[60:63]
	v_mfma_f32_16x16x32_bf16 v[48:51], v[158:161], v[220:223], v[48:51]
	v_mfma_f32_16x16x32_bf16 v[44:47], v[170:173], v[220:223], v[44:47]
	v_mfma_f32_16x16x32_bf16 v[32:35], v[158:161], v[228:231], v[32:35]
	v_mfma_f32_16x16x32_bf16 v[28:31], v[170:173], v[228:231], v[28:31]
	v_mfma_f32_16x16x32_bf16 v[16:19], v[158:161], v[236:239], v[16:19]
	v_mfma_f32_16x16x32_bf16 v[12:15], v[170:173], v[236:239], v[12:15]
	v_mfma_f32_16x16x32_bf16 v[64:67], v[166:169], v[216:219], v[64:67]
	v_mfma_f32_16x16x32_bf16 v[60:63], v[174:177], v[216:219], v[60:63]
	v_mfma_f32_16x16x32_bf16 v[48:51], v[166:169], v[224:227], v[48:51]
	v_mfma_f32_16x16x32_bf16 v[44:47], v[174:177], v[224:227], v[44:47]
	v_mfma_f32_16x16x32_bf16 v[32:35], v[166:169], v[232:235], v[32:35]
	v_mfma_f32_16x16x32_bf16 v[28:31], v[174:177], v[232:235], v[28:31]
	v_mfma_f32_16x16x32_bf16 v[16:19], v[166:169], v[240:243], v[16:19]
	v_mfma_f32_16x16x32_bf16 v[12:15], v[174:177], v[240:243], v[12:15]
	v_mfma_f32_16x16x32_bf16 v[56:59], v[178:181], v[212:215], v[56:59]
	v_mfma_f32_16x16x32_bf16 v[52:55], v[186:189], v[212:215], v[52:55]
	v_mfma_f32_16x16x32_bf16 v[40:43], v[178:181], v[220:223], v[40:43]
	v_mfma_f32_16x16x32_bf16 v[36:39], v[186:189], v[220:223], v[36:39]
	v_mfma_f32_16x16x32_bf16 v[24:27], v[178:181], v[228:231], v[24:27]
	v_mfma_f32_16x16x32_bf16 v[20:23], v[186:189], v[228:231], v[20:23]
	v_mfma_f32_16x16x32_bf16 v[8:11], v[178:181], v[236:239], v[8:11]
	v_mfma_f32_16x16x32_bf16 v[4:7], v[186:189], v[236:239], v[4:7]
	v_mfma_f32_16x16x32_bf16 v[56:59], v[182:185], v[216:219], v[56:59]
	v_mfma_f32_16x16x32_bf16 v[52:55], v[190:193], v[216:219], v[52:55]
	v_mfma_f32_16x16x32_bf16 v[40:43], v[182:185], v[224:227], v[40:43]
	v_mfma_f32_16x16x32_bf16 v[36:39], v[190:193], v[224:227], v[36:39]
	v_mfma_f32_16x16x32_bf16 v[24:27], v[182:185], v[232:235], v[24:27]
	v_mfma_f32_16x16x32_bf16 v[20:23], v[190:193], v[232:235], v[20:23]
	v_mfma_f32_16x16x32_bf16 v[8:11], v[182:185], v[240:243], v[8:11]
	v_mfma_f32_16x16x32_bf16 v[4:7], v[190:193], v[240:243], v[4:7]
	s_setprio 0
	s_barrier
	s_add_i32 s80, s80, 2
	s_add_u32 s26, s26, 0x100
	s_addc_u32 s27, s27, 0
	s_add_u32 s76, s76, 0x100
	s_addc_u32 s77, s77, 0
	s_cmp_gt_u32 s80, 29
	s_cbranch_scc0 .LBB0_1741
	s_and_b64 vcc, exec, s[16:17]
	s_cbranch_vccz .LBB0_1744
	s_barrier

; #define PG8_STAGE(bufoff, gbase, voff) do { _Pragma("unroll") for (int _i = 0; _i < 2; ++_i) \
;         __builtin_amdgcn_global_load_lds((const unsigned*)((const char*)(gbase) + (voff)[_i]), (LAS unsigned*)(lds + (bufoff) + ldsw + _i * 8192), 16, 0, 0); } while (0)
; #define PG8_LDA(dst, b, h) do { _Pragma("unroll") for (int m = 0; m < 4; ++m) _Pragma("unroll") for (int k = 0; k < 2; ++k) dst[m][k] = *(const LAS bf16x8*)(lds + PG8_SA(b, h) + aoff + m * 2048 + k * 1024); } while (0)
; #define PG8_LDB(dst, b, h) do { _Pragma("unroll") for (int n = 0; n < 2; ++n) _Pragma("unroll") for (int k = 0; k < 2; ++k) dst[n][k] = *(const LAS bf16x8*)(lds + PG8_SB(b, h) + boff + n * 2048 + k * 1024); } while (0)
; #define PG8_MMA(ai, bj, At, Bt) do { __builtin_amdgcn_s_setprio(1); _Pragma("unroll") for (int m = 0; m < 4; ++m) _Pragma("unroll") for (int n = 0; n < 2; ++n) _Pragma("unroll") for (int k = 0; k < 2; ++k) \
;         acc[ai][bj][m][n] = __builtin_amdgcn_mfma_f32_16x16x32_bf16(Bt[n][k], At[m][k], acc[ai][bj][m][n], 0, 0, 0); __builtin_amdgcn_s_setprio(0); } while (0)
; #define PG8_WAIT_V(n) asm volatile("s_waitcnt vmcnt(" #n ")" ::: "memory")
; #define PG8_WAIT_L(n) asm volatile("s_waitcnt lgkmcnt(" #n ")" ::: "memory")
; #define PG8_BAR __builtin_amdgcn_s_barrier()
; #define PG8_SCHED __builtin_amdgcn_sched_barrier(0)
; template <class Epi>
; __device__ __forceinline__ void gemm_phase(LAS unsigned char* lds, const Gemm g, const StaticOrder& S, const Epi& E) {
;     ...
;         for (int t = 0; t < nt; t += 2) {
;             const bool last = (t == nt - 2);
;             const char* a1 = cA + (size_t)(t + 1) * kstep;
;             const char* a2 = last ? nA : cA + (size_t)(t + 2) * kstep; const char* b2 = last ? nB : cB + (size_t)(t + 2) * kstep;
;             const char* a3 = a2 + kstep; const char* b3 = b2 + kstep;
;             PG8_LDB(B0, 0, 0); PG8_LDB(B1, 0, 1); PG8_SCHED; PG8_LDA(At, 0, 0); PG8_STAGE(PG8_SA(1, 1), a1 + hstep, voffA);
;             PG8_WAIT_V(8); PG8_WAIT_L(0); PG8_BAR; PG8_MMA(0, 0, At, B0); PG8_MMA(0, 1, At, B1); PG8_BAR; PG8_SCHED;
;             PG8_LDA(At, 0, 1); PG8_STAGE(PG8_SB(0, 0), b2, voffB); PG8_STAGE(PG8_SB(0, 1), b2 + hstep, voffB); PG8_STAGE(PG8_SA(0, 0), a2, voffA);
;             PG8_WAIT_V(8); PG8_WAIT_L(0); PG8_BAR; PG8_MMA(1, 0, At, B0); PG8_MMA(1, 1, At, B1); PG8_BAR; PG8_SCHED;
.LBB0_1826:
	s_add_u32 s26, s24, 0xfff80080
	s_addc_u32 s27, s25, -1
	s_add_i32 s77, 0, 0x10000
	s_cmp_eq_u32 s76, 28
	s_cselect_b32 s29, s19, s27
	s_cselect_b32 s28, s45, s26
	s_cselect_b32 s27, s17, s75
	s_cselect_b32 s26, s55, s74
	s_add_i32 s80, 0, 0x14000
	v_add_u32_e32 v174, s77, v147
	v_add_u32_e32 v190, s80, v147
	ds_read_b128 v[158:161], v174
	ds_read_b128 v[166:169], v174 offset:1024
	ds_read_b128 v[170:173], v174 offset:2048
	ds_read_b128 v[174:177], v174 offset:3072
	ds_read_b128 v[178:181], v190
	ds_read_b128 v[182:185], v190 offset:1024
	ds_read_b128 v[186:189], v190 offset:2048
	ds_read_b128 v[190:193], v190 offset:3072
	v_lshl_add_u64 v[198:199], s[24:25], 0, v[140:141]
	s_add_i32 m0, s31, 0xc000
	ds_read_b128 v[212:215], v165
	ds_read_b128 v[216:219], v165 offset:1024
	ds_read_b128 v[220:223], v165 offset:2048
	ds_read_b128 v[224:227], v165 offset:3072
	ds_read_b128 v[228:231], v165 offset:4096
	ds_read_b128 v[232:235], v165 offset:5120
	ds_read_b128 v[236:239], v165 offset:6144
	ds_read_b128 v[240:243], v165 offset:7168
	global_load_lds_dwordx4 v[198:199], off
	v_lshl_add_u64 v[198:199], s[24:25], 0, v[156:157]
	s_add_i32 m0, s31, 0xe000
	s_nop 0
	global_load_lds_dwordx4 v[198:199], off
	s_waitcnt vmcnt(8)
	s_waitcnt lgkmcnt(0)
	s_barrier
	s_setprio 1
	s_waitcnt lgkmcnt(0)
	v_mfma_f32_16x16x32_bf16 v[128:131], v[158:161], v[212:215], v[128:131]
	v_mfma_f32_16x16x32_bf16 v[124:127], v[170:173], v[212:215], v[124:127]
	v_mfma_f32_16x16x32_bf16 v[112:115], v[158:161], v[220:223], v[112:115]
	v_mfma_f32_16x16x32_bf16 v[108:111], v[170:173], v[220:223], v[108:111]
	v_mfma_f32_16x16x32_bf16 v[96:99], v[158:161], v[228:231], v[96:99]
	v_mfma_f32_16x16x32_bf16 v[92:95], v[170:173], v[228:231], v[92:95]
	v_mfma_f32_16x16x32_bf16 v[80:83], v[158:161], v[236:239], v[80:83]
	v_mfma_f32_16x16x32_bf16 v[76:79], v[170:173], v[236:239], v[76:79]
	v_mfma_f32_16x16x32_bf16 v[128:131], v[166:169], v[216:219], v[128:131]
	v_mfma_f32_16x16x32_bf16 v[124:127], v[174:177], v[216:219], v[124:127]
	v_mfma_f32_16x16x32_bf16 v[112:115], v[166:169], v[224:227], v[112:115]
	v_mfma_f32_16x16x32_bf16 v[108:111], v[174:177], v[224:227], v[108:111]
	v_mfma_f32_16x16x32_bf16 v[96:99], v[166:169], v[232:235], v[96:99]
	v_mfma_f32_16x16x32_bf16 v[92:95], v[174:177], v[232:235], v[92:95]
	v_mfma_f32_16x16x32_bf16 v[80:83], v[166:169], v[240:243], v[80:83]
	v_mfma_f32_16x16x32_bf16 v[76:79], v[174:177], v[240:243], v[76:79]
	v_mfma_f32_16x16x32_bf16 v[120:123], v[178:181], v[212:215], v[120:123]
	v_mfma_f32_16x16x32_bf16 v[116:119], v[186:189], v[212:215], v[116:119]
	v_mfma_f32_16x16x32_bf16 v[104:107], v[178:181], v[220:223], v[104:107]
	v_mfma_f32_16x16x32_bf16 v[100:103], v[186:189], v[220:223], v[100:103]
	v_mfma_f32_16x16x32_bf16 v[88:91], v[178:181], v[228:231], v[88:91]
	v_mfma_f32_16x16x32_bf16 v[84:87], v[186:189], v[228:231], v[84:87]
	v_mfma_f32_16x16x32_bf16 v[72:75], v[178:181], v[236:239], v[72:75]
	v_mfma_f32_16x16x32_bf16 v[68:71], v[186:189], v[236:239], v[68:71]
	v_mfma_f32_16x16x32_bf16 v[120:123], v[182:185], v[216:219], v[120:123]
	v_mfma_f32_16x16x32_bf16 v[116:119], v[190:193], v[216:219], v[116:119]
	v_mfma_f32_16x16x32_bf16 v[104:107], v[182:185], v[224:227], v[104:107]
	v_mfma_f32_16x16x32_bf16 v[100:103], v[190:193], v[224:227], v[100:103]
	v_mfma_f32_16x16x32_bf16 v[88:91], v[182:185], v[232:235], v[88:91]
	v_mfma_f32_16x16x32_bf16 v[84:87], v[190:193], v[232:235], v[84:87]
	v_mfma_f32_16x16x32_bf16 v[72:75], v[182:185], v[240:243], v[72:75]
	v_mfma_f32_16x16x32_bf16 v[68:71], v[190:193], v[240:243], v[68:71]
	s_setprio 0
	s_barrier
	s_add_i32 s77, s77, s30
	v_lshl_add_u64 v[198:199], s[26:27], 0, v[136:137]
	s_mov_b32 m0, s77
	ds_read_b128 v[212:215], v165 offset:16384
	ds_read_b128 v[216:219], v165 offset:17408
	ds_read_b128 v[220:223], v165 offset:18432
	ds_read_b128 v[224:227], v165 offset:19456
	ds_read_b128 v[228:231], v165 offset:20480
	ds_read_b128 v[232:235], v165 offset:21504
	ds_read_b128 v[236:239], v165 offset:22528
	ds_read_b128 v[240:243], v165 offset:23552
	global_load_lds_dwordx4 v[198:199], off
	s_add_i32 m0, s77, 0x2000
	s_add_u32 s78, s26, 0x80000
	v_lshl_add_u64 v[244:245], s[26:27], 0, v[132:133]
	s_addc_u32 s79, s27, 0
	s_add_i32 s77, s80, s30
	global_load_lds_dwordx4 v[244:245], off
	v_lshl_add_u64 v[246:247], s[78:79], 0, v[136:137]
	s_mov_b32 m0, s77
	v_lshl_add_u64 v[248:249], s[28:29], 0, v[134:135]
	global_load_lds_dwordx4 v[246:247], off
	v_lshl_add_u64 v[246:247], s[78:79], 0, v[132:133]
	s_add_i32 m0, s77, 0x2000
	s_nop 0
	global_load_lds_dwordx4 v[246:247], off
	v_lshl_add_u64 v[246:247], s[28:29], 0, v[138:139]
	s_mov_b32 m0, s31
	s_nop 0
	global_load_lds_dwordx4 v[246:247], off
	s_mov_b32 m0, s34
	s_nop 0
	global_load_lds_dwordx4 v[248:249], off
	s_waitcnt vmcnt(8)
	s_waitcnt lgkmcnt(0)
	s_barrier
; #define PG8_STAGE(bufoff, gbase, voff) do { _Pragma("unroll") for (int _i = 0; _i < 2; ++_i) \
;         __builtin_amdgcn_global_load_lds((const unsigned*)((const char*)(gbase) + (voff)[_i]), (LAS unsigned*)(lds + (bufoff) + ldsw + _i * 8192), 16, 0, 0); } while (0)
; #define PG8_LDA(dst, b, h) do { _Pragma("unroll") for (int m = 0; m < 4; ++m) _Pragma("unroll") for (int k = 0; k < 2; ++k) dst[m][k] = *(const LAS bf16x8*)(lds + PG8_SA(b, h) + aoff + m * 2048 + k * 1024); } while (0)
; #define PG8_LDB(dst, b, h) do { _Pragma("unroll") for (int n = 0; n < 2; ++n) _Pragma("unroll") for (int k = 0; k < 2; ++k) dst[n][k] = *(const LAS bf16x8*)(lds + PG8_SB(b, h) + boff + n * 2048 + k * 1024); } while (0)
; #define PG8_MMA(ai, bj, At, Bt) do { __builtin_amdgcn_s_setprio(1); _Pragma("unroll") for (int m = 0; m < 4; ++m) _Pragma("unroll") for (int n = 0; n < 2; ++n) _Pragma("unroll") for (int k = 0; k < 2; ++k) \
;         acc[ai][bj][m][n] = __builtin_amdgcn_mfma_f32_16x16x32_bf16(Bt[n][k], At[m][k], acc[ai][bj][m][n], 0, 0, 0); __builtin_amdgcn_s_setprio(0); } while (0)
; #define PG8_WAIT_V(n) asm volatile("s_waitcnt vmcnt(" #n ")" ::: "memory")
; #define PG8_WAIT_L(n) asm volatile("s_waitcnt lgkmcnt(" #n ")" ::: "memory")
; #define PG8_BAR __builtin_amdgcn_s_barrier()
; #define PG8_SCHED __builtin_amdgcn_sched_barrier(0)
; template <class Epi>
; __device__ __forceinline__ void gemm_phase(LAS unsigned char* lds, const Gemm g, const StaticOrder& S, const Epi& E) {
;     ...
;             PG8_LDA(At, 0, 1); PG8_STAGE(PG8_SB(0, 0), b2, voffB); PG8_STAGE(PG8_SB(0, 1), b2 + hstep, voffB); PG8_STAGE(PG8_SA(0, 0), a2, voffA);
;             PG8_WAIT_V(8); PG8_WAIT_L(0); PG8_BAR; PG8_MMA(1, 0, At, B0); PG8_MMA(1, 1, At, B1); PG8_BAR; PG8_SCHED;
;             PG8_LDB(B0, 1, 0); PG8_LDB(B1, 1, 1); PG8_SCHED; PG8_LDA(At, 1, 0); PG8_STAGE(PG8_SA(0, 1), a2 + hstep, voffA);
;             PG8_WAIT_V(8); PG8_WAIT_L(0); PG8_BAR; PG8_MMA(0, 0, At, B0); PG8_MMA(0, 1, At, B1); PG8_BAR; PG8_SCHED;
	s_setprio 1
	s_waitcnt lgkmcnt(0)
	v_mfma_f32_16x16x32_bf16 v[64:67], v[158:161], v[212:215], v[64:67]
	v_mfma_f32_16x16x32_bf16 v[60:63], v[170:173], v[212:215], v[60:63]
	v_mfma_f32_16x16x32_bf16 v[56:59], v[158:161], v[220:223], v[56:59]
	v_mfma_f32_16x16x32_bf16 v[48:51], v[170:173], v[220:223], v[48:51]
	v_mfma_f32_16x16x32_bf16 v[40:43], v[158:161], v[228:231], v[40:43]
	v_mfma_f32_16x16x32_bf16 v[32:35], v[170:173], v[228:231], v[32:35]
	v_mfma_f32_16x16x32_bf16 v[20:23], v[158:161], v[236:239], v[20:23]
	v_mfma_f32_16x16x32_bf16 v[12:15], v[170:173], v[236:239], v[12:15]
	v_mfma_f32_16x16x32_bf16 v[64:67], v[166:169], v[216:219], v[64:67]
	v_mfma_f32_16x16x32_bf16 v[60:63], v[174:177], v[216:219], v[60:63]
	v_mfma_f32_16x16x32_bf16 v[56:59], v[166:169], v[224:227], v[56:59]
	v_mfma_f32_16x16x32_bf16 v[48:51], v[174:177], v[224:227], v[48:51]
	v_mfma_f32_16x16x32_bf16 v[40:43], v[166:169], v[232:235], v[40:43]
	v_mfma_f32_16x16x32_bf16 v[32:35], v[174:177], v[232:235], v[32:35]
	v_mfma_f32_16x16x32_bf16 v[20:23], v[166:169], v[240:243], v[20:23]
	v_mfma_f32_16x16x32_bf16 v[12:15], v[174:177], v[240:243], v[12:15]
	v_mfma_f32_16x16x32_bf16 v[52:55], v[178:181], v[212:215], v[52:55]
	v_mfma_f32_16x16x32_bf16 v[44:47], v[186:189], v[212:215], v[44:47]
	v_mfma_f32_16x16x32_bf16 v[36:39], v[178:181], v[220:223], v[36:39]
	v_mfma_f32_16x16x32_bf16 v[28:31], v[186:189], v[220:223], v[28:31]
	v_mfma_f32_16x16x32_bf16 v[24:27], v[178:181], v[228:231], v[24:27]
	v_mfma_f32_16x16x32_bf16 v[16:19], v[186:189], v[228:231], v[16:19]
	v_mfma_f32_16x16x32_bf16 v[8:11], v[178:181], v[236:239], v[8:11]
	v_mfma_f32_16x16x32_bf16 v[4:7], v[186:189], v[236:239], v[4:7]
	v_mfma_f32_16x16x32_bf16 v[52:55], v[182:185], v[216:219], v[52:55]
	v_mfma_f32_16x16x32_bf16 v[44:47], v[190:193], v[216:219], v[44:47]
	v_mfma_f32_16x16x32_bf16 v[36:39], v[182:185], v[224:227], v[36:39]
	v_mfma_f32_16x16x32_bf16 v[28:31], v[190:193], v[224:227], v[28:31]
	v_mfma_f32_16x16x32_bf16 v[24:27], v[182:185], v[232:235], v[24:27]
	v_mfma_f32_16x16x32_bf16 v[16:19], v[190:193], v[232:235], v[16:19]
	v_mfma_f32_16x16x32_bf16 v[8:11], v[182:185], v[240:243], v[8:11]
	v_mfma_f32_16x16x32_bf16 v[4:7], v[190:193], v[240:243], v[4:7]
	s_setprio 0
	s_barrier
	s_add_i32 s77, 0, 0x18000
	s_add_i32 s78, 0, 0x1c000
	v_add_u32_e32 v174, s77, v147
	v_add_u32_e32 v190, s78, v147
	ds_read_b128 v[158:161], v174
	ds_read_b128 v[166:169], v174 offset:1024
	ds_read_b128 v[170:173], v174 offset:2048
	ds_read_b128 v[174:177], v174 offset:3072
	ds_read_b128 v[178:181], v190
	ds_read_b128 v[182:185], v190 offset:1024
	ds_read_b128 v[186:189], v190 offset:2048
	ds_read_b128 v[190:193], v190 offset:3072
	s_add_u32 s28, s28, 0x80000
	s_addc_u32 s29, s29, 0
	s_mov_b32 m0, s35
	v_lshl_add_u64 v[250:251], s[28:29], 0, v[138:139]
	ds_read_b128 v[212:215], v165 offset:32768
	ds_read_b128 v[216:219], v165 offset:33792
	ds_read_b128 v[220:223], v165 offset:34816
	ds_read_b128 v[224:227], v165 offset:35840
	ds_read_b128 v[228:231], v165 offset:36864
	ds_read_b128 v[232:235], v165 offset:37888
	ds_read_b128 v[236:239], v165 offset:38912
	ds_read_b128 v[240:243], v165 offset:39936
	global_load_lds_dwordx4 v[250:251], off
	v_lshl_add_u64 v[250:251], s[28:29], 0, v[134:135]
	s_mov_b32 m0, s36
	s_nop 0
	global_load_lds_dwordx4 v[250:251], off
	s_waitcnt vmcnt(8)
	s_waitcnt lgkmcnt(0)
	s_barrier
	s_setprio 1
	s_waitcnt lgkmcnt(0)
	v_mfma_f32_16x16x32_bf16 v[128:131], v[158:161], v[212:215], v[128:131]
	v_mfma_f32_16x16x32_bf16 v[124:127], v[170:173], v[212:215], v[124:127]
	v_mfma_f32_16x16x32_bf16 v[112:115], v[158:161], v[220:223], v[112:115]
	v_mfma_f32_16x16x32_bf16 v[108:111], v[170:173], v[220:223], v[108:111]
	v_mfma_f32_16x16x32_bf16 v[96:99], v[158:161], v[228:231], v[96:99]
	v_mfma_f32_16x16x32_bf16 v[92:95], v[170:173], v[228:231], v[92:95]
	v_mfma_f32_16x16x32_bf16 v[80:83], v[158:161], v[236:239], v[80:83]
	v_mfma_f32_16x16x32_bf16 v[76:79], v[170:173], v[236:239], v[76:79]
	v_mfma_f32_16x16x32_bf16 v[128:131], v[166:169], v[216:219], v[128:131]
	v_mfma_f32_16x16x32_bf16 v[124:127], v[174:177], v[216:219], v[124:127]
	v_mfma_f32_16x16x32_bf16 v[112:115], v[166:169], v[224:227], v[112:115]
	v_mfma_f32_16x16x32_bf16 v[108:111], v[174:177], v[224:227], v[108:111]
	v_mfma_f32_16x16x32_bf16 v[96:99], v[166:169], v[232:235], v[96:99]
	v_mfma_f32_16x16x32_bf16 v[92:95], v[174:177], v[232:235], v[92:95]
	v_mfma_f32_16x16x32_bf16 v[80:83], v[166:169], v[240:243], v[80:83]
	v_mfma_f32_16x16x32_bf16 v[76:79], v[174:177], v[240:243], v[76:79]
	v_mfma_f32_16x16x32_bf16 v[120:123], v[178:181], v[212:215], v[120:123]
	v_mfma_f32_16x16x32_bf16 v[116:119], v[186:189], v[212:215], v[116:119]
	v_mfma_f32_16x16x32_bf16 v[104:107], v[178:181], v[220:223], v[104:107]
	v_mfma_f32_16x16x32_bf16 v[100:103], v[186:189], v[220:223], v[100:103]
	v_mfma_f32_16x16x32_bf16 v[88:91], v[178:181], v[228:231], v[88:91]
	v_mfma_f32_16x16x32_bf16 v[84:87], v[186:189], v[228:231], v[84:87]
	v_mfma_f32_16x16x32_bf16 v[72:75], v[178:181], v[236:239], v[72:75]
	v_mfma_f32_16x16x32_bf16 v[68:71], v[186:189], v[236:239], v[68:71]
	v_mfma_f32_16x16x32_bf16 v[120:123], v[182:185], v[216:219], v[120:123]
	v_mfma_f32_16x16x32_bf16 v[116:119], v[190:193], v[216:219], v[116:119]
	v_mfma_f32_16x16x32_bf16 v[104:107], v[182:185], v[224:227], v[104:107]
	v_mfma_f32_16x16x32_bf16 v[100:103], v[190:193], v[224:227], v[100:103]
	v_mfma_f32_16x16x32_bf16 v[88:91], v[182:185], v[232:235], v[88:91]
	v_mfma_f32_16x16x32_bf16 v[84:87], v[190:193], v[232:235], v[84:87]
	v_mfma_f32_16x16x32_bf16 v[72:75], v[182:185], v[240:243], v[72:75]
	v_mfma_f32_16x16x32_bf16 v[68:71], v[190:193], v[240:243], v[68:71]
	s_setprio 0
	s_barrier
; #define PG8_STAGE(bufoff, gbase, voff) do { _Pragma("unroll") for (int _i = 0; _i < 2; ++_i) \
;         __builtin_amdgcn_global_load_lds((const unsigned*)((const char*)(gbase) + (voff)[_i]), (LAS unsigned*)(lds + (bufoff) + ldsw + _i * 8192), 16, 0, 0); } while (0)
; #define PG8_LDA(dst, b, h) do { _Pragma("unroll") for (int m = 0; m < 4; ++m) _Pragma("unroll") for (int k = 0; k < 2; ++k) dst[m][k] = *(const LAS bf16x8*)(lds + PG8_SA(b, h) + aoff + m * 2048 + k * 1024); } while (0)
; #define PG8_MMA(ai, bj, At, Bt) do { __builtin_amdgcn_s_setprio(1); _Pragma("unroll") for (int m = 0; m < 4; ++m) _Pragma("unroll") for (int n = 0; n < 2; ++n) _Pragma("unroll") for (int k = 0; k < 2; ++k) \
;         acc[ai][bj][m][n] = __builtin_amdgcn_mfma_f32_16x16x32_bf16(Bt[n][k], At[m][k], acc[ai][bj][m][n], 0, 0, 0); __builtin_amdgcn_s_setprio(0); } while (0)
; #define PG8_WAIT_V(n) asm volatile("s_waitcnt vmcnt(" #n ")" ::: "memory")
; #define PG8_WAIT_L(n) asm volatile("s_waitcnt lgkmcnt(" #n ")" ::: "memory")
; #define PG8_BAR __builtin_amdgcn_s_barrier()
; #define PG8_SCHED __builtin_amdgcn_sched_barrier(0)
; template <class Epi>
; __device__ __forceinline__ void gemm_phase(LAS unsigned char* lds, const Gemm g, const StaticOrder& S, const Epi& E) {
;     ...
;             PG8_LDA(At, 1, 1); PG8_STAGE(PG8_SB(1, 0), b3, voffB); PG8_STAGE(PG8_SB(1, 1), b3 + hstep, voffB); PG8_STAGE(PG8_SA(1, 0), a3, voffA);
;             PG8_WAIT_V(8); PG8_WAIT_L(0); PG8_BAR; PG8_MMA(1, 0, At, B0); PG8_MMA(1, 1, At, B1); PG8_BAR; PG8_SCHED;
;         }
;         if (wr == 0) PG8_BAR;
	s_add_i32 s28, s77, s30
	v_lshl_add_u64 v[198:199], v[198:199], 0, s[68:69]
	s_mov_b32 m0, s28
	ds_read_b128 v[212:215], v165 offset:49152
	ds_read_b128 v[216:219], v165 offset:50176
	ds_read_b128 v[220:223], v165 offset:51200
	ds_read_b128 v[224:227], v165 offset:52224
	ds_read_b128 v[228:231], v165 offset:53248
	ds_read_b128 v[232:235], v165 offset:54272
	ds_read_b128 v[236:239], v165 offset:55296
	ds_read_b128 v[240:243], v165 offset:56320
	global_load_lds_dwordx4 v[198:199], off
	s_add_i32 m0, s28, 0x2000
	s_add_u32 s26, s26, 0x80080
	v_lshl_add_u64 v[198:199], v[244:245], 0, s[68:69]
	s_addc_u32 s27, s27, 0
	s_add_i32 s28, s78, s30
	global_load_lds_dwordx4 v[198:199], off
	v_lshl_add_u64 v[198:199], s[26:27], 0, v[136:137]
	s_mov_b32 m0, s28
	s_nop 0
	global_load_lds_dwordx4 v[198:199], off
	v_lshl_add_u64 v[198:199], s[26:27], 0, v[132:133]
	s_add_i32 m0, s28, 0x2000
	s_nop 0
	global_load_lds_dwordx4 v[198:199], off
	v_lshl_add_u64 v[198:199], v[246:247], 0, s[68:69]
	s_mov_b32 m0, s37
	s_nop 0
	global_load_lds_dwordx4 v[198:199], off
	v_lshl_add_u64 v[198:199], v[248:249], 0, s[68:69]
	s_mov_b32 m0, s38
	s_nop 0
	global_load_lds_dwordx4 v[198:199], off
	s_waitcnt vmcnt(8)
	s_waitcnt lgkmcnt(0)
	s_barrier
	s_setprio 1
	s_waitcnt lgkmcnt(0)
	v_mfma_f32_16x16x32_bf16 v[64:67], v[158:161], v[212:215], v[64:67]
	v_mfma_f32_16x16x32_bf16 v[60:63], v[170:173], v[212:215], v[60:63]
	v_mfma_f32_16x16x32_bf16 v[56:59], v[158:161], v[220:223], v[56:59]
	v_mfma_f32_16x16x32_bf16 v[48:51], v[170:173], v[220:223], v[48:51]
	v_mfma_f32_16x16x32_bf16 v[40:43], v[158:161], v[228:231], v[40:43]
	v_mfma_f32_16x16x32_bf16 v[32:35], v[170:173], v[228:231], v[32:35]
	v_mfma_f32_16x16x32_bf16 v[20:23], v[158:161], v[236:239], v[20:23]
	v_mfma_f32_16x16x32_bf16 v[12:15], v[170:173], v[236:239], v[12:15]
	v_mfma_f32_16x16x32_bf16 v[64:67], v[166:169], v[216:219], v[64:67]
	v_mfma_f32_16x16x32_bf16 v[60:63], v[174:177], v[216:219], v[60:63]
	v_mfma_f32_16x16x32_bf16 v[56:59], v[166:169], v[224:227], v[56:59]
	v_mfma_f32_16x16x32_bf16 v[48:51], v[174:177], v[224:227], v[48:51]
	v_mfma_f32_16x16x32_bf16 v[40:43], v[166:169], v[232:235], v[40:43]
	v_mfma_f32_16x16x32_bf16 v[32:35], v[174:177], v[232:235], v[32:35]
	v_mfma_f32_16x16x32_bf16 v[20:23], v[166:169], v[240:243], v[20:23]
	v_mfma_f32_16x16x32_bf16 v[12:15], v[174:177], v[240:243], v[12:15]
	v_mfma_f32_16x16x32_bf16 v[52:55], v[178:181], v[212:215], v[52:55]
	v_mfma_f32_16x16x32_bf16 v[44:47], v[186:189], v[212:215], v[44:47]
	v_mfma_f32_16x16x32_bf16 v[36:39], v[178:181], v[220:223], v[36:39]
	v_mfma_f32_16x16x32_bf16 v[28:31], v[186:189], v[220:223], v[28:31]
	v_mfma_f32_16x16x32_bf16 v[24:27], v[178:181], v[228:231], v[24:27]
	v_mfma_f32_16x16x32_bf16 v[16:19], v[186:189], v[228:231], v[16:19]
	v_mfma_f32_16x16x32_bf16 v[8:11], v[178:181], v[236:239], v[8:11]
	v_mfma_f32_16x16x32_bf16 v[4:7], v[186:189], v[236:239], v[4:7]
	v_mfma_f32_16x16x32_bf16 v[52:55], v[182:185], v[216:219], v[52:55]
	v_mfma_f32_16x16x32_bf16 v[44:47], v[190:193], v[216:219], v[44:47]
	v_mfma_f32_16x16x32_bf16 v[36:39], v[182:185], v[224:227], v[36:39]
	v_mfma_f32_16x16x32_bf16 v[28:31], v[190:193], v[224:227], v[28:31]
	v_mfma_f32_16x16x32_bf16 v[24:27], v[182:185], v[232:235], v[24:27]
	v_mfma_f32_16x16x32_bf16 v[16:19], v[190:193], v[232:235], v[16:19]
	v_mfma_f32_16x16x32_bf16 v[8:11], v[182:185], v[240:243], v[8:11]
	v_mfma_f32_16x16x32_bf16 v[4:7], v[190:193], v[240:243], v[4:7]
	s_setprio 0
	s_barrier
	s_add_i32 s76, s76, 2
	s_add_u32 s24, s24, 0x100
	s_addc_u32 s25, s25, 0
	s_add_u32 s74, s74, 0x100
	s_addc_u32 s75, s75, 0
	s_cmp_gt_u32 s76, 29
	s_cbranch_scc0 .LBB0_1826
	s_and_b64 vcc, exec, s[14:15]
	s_cbranch_vccz .LBB0_1829
	s_barrier

; #define PG8_STAGE(bufoff, gbase, voff) do { _Pragma("unroll") for (int _i = 0; _i < 2; ++_i) \
;         __builtin_amdgcn_global_load_lds((const unsigned*)((const char*)(gbase) + (voff)[_i]), (LAS unsigned*)(lds + (bufoff) + ldsw + _i * 8192), 16, 0, 0); } while (0)
; #define PG8_LDA(dst, b, h) do { _Pragma("unroll") for (int m = 0; m < 4; ++m) _Pragma("unroll") for (int k = 0; k < 2; ++k) dst[m][k] = *(const LAS bf16x8*)(lds + PG8_SA(b, h) + aoff + m * 2048 + k * 1024); } while (0)
; #define PG8_LDB(dst, b, h) do { _Pragma("unroll") for (int n = 0; n < 2; ++n) _Pragma("unroll") for (int k = 0; k < 2; ++k) dst[n][k] = *(const LAS bf16x8*)(lds + PG8_SB(b, h) + boff + n * 2048 + k * 1024); } while (0)
; #define PG8_MMA(ai, bj, At, Bt) do { __builtin_amdgcn_s_setprio(1); _Pragma("unroll") for (int m = 0; m < 4; ++m) _Pragma("unroll") for (int n = 0; n < 2; ++n) _Pragma("unroll") for (int k = 0; k < 2; ++k) \
;         acc[ai][bj][m][n] = __builtin_amdgcn_mfma_f32_16x16x32_bf16(Bt[n][k], At[m][k], acc[ai][bj][m][n], 0, 0, 0); __builtin_amdgcn_s_setprio(0); } while (0)
; #define PG8_WAIT_V(n) asm volatile("s_waitcnt vmcnt(" #n ")" ::: "memory")
; #define PG8_WAIT_L(n) asm volatile("s_waitcnt lgkmcnt(" #n ")" ::: "memory")
; #define PG8_BAR __builtin_amdgcn_s_barrier()
; #define PG8_SCHED __builtin_amdgcn_sched_barrier(0)
; template <class Epi>
; __device__ __forceinline__ void gemm_phase(LAS unsigned char* lds, const Gemm g, const StaticOrder& S, const Epi& E) {
;     ...
;         for (int t = 0; t < nt; t += 2) {
;             const bool last = (t == nt - 2);
;             const char* a1 = cA + (size_t)(t + 1) * kstep;
;             const char* a2 = last ? nA : cA + (size_t)(t + 2) * kstep; const char* b2 = last ? nB : cB + (size_t)(t + 2) * kstep;
;             const char* a3 = a2 + kstep; const char* b3 = b2 + kstep;
;             PG8_LDB(B0, 0, 0); PG8_LDB(B1, 0, 1); PG8_SCHED; PG8_LDA(At, 0, 0); PG8_STAGE(PG8_SA(1, 1), a1 + hstep, voffA);
;             PG8_WAIT_V(8); PG8_WAIT_L(0); PG8_BAR; PG8_MMA(0, 0, At, B0); PG8_MMA(0, 1, At, B1); PG8_BAR; PG8_SCHED;
;             PG8_LDA(At, 0, 1); PG8_STAGE(PG8_SB(0, 0), b2, voffB); PG8_STAGE(PG8_SB(0, 1), b2 + hstep, voffB); PG8_STAGE(PG8_SA(0, 0), a2, voffA);
;             PG8_WAIT_V(8); PG8_WAIT_L(0); PG8_BAR; PG8_MMA(1, 0, At, B0); PG8_MMA(1, 1, At, B1); PG8_BAR; PG8_SCHED;
.LBB0_1972:
	s_add_u32 s24, s22, 0xffe00080
	s_addc_u32 s25, s23, -1
	s_add_i32 s75, 0, 0x10000
	s_cmpk_eq_i32 s74, 0x7c
	s_cselect_b32 s27, s17, s25
	s_cselect_b32 s26, s45, s24
	v_add_u32_e32 v162, s75, v147
	s_cselect_b32 s25, s15, s61
	s_cselect_b32 s24, s55, s60
	s_add_i32 s78, 0, 0x14000
	ds_read_b128 v[158:161], v162
	ds_read_b128 v[166:169], v162 offset:1024
	ds_read_b128 v[170:173], v162 offset:2048
	ds_read_b128 v[174:177], v162 offset:3072
	v_add_u32_e32 v162, s78, v147
	ds_read_b128 v[178:181], v162
	ds_read_b128 v[182:185], v162 offset:1024
	ds_read_b128 v[186:189], v162 offset:2048
	ds_read_b128 v[190:193], v162 offset:3072
	v_lshl_add_u64 v[162:163], s[22:23], 0, v[140:141]
	s_add_i32 m0, s31, 0xc000
	ds_read_b128 v[212:215], v165
	ds_read_b128 v[216:219], v165 offset:1024
	ds_read_b128 v[220:223], v165 offset:2048
	ds_read_b128 v[224:227], v165 offset:3072
	ds_read_b128 v[228:231], v165 offset:4096
	ds_read_b128 v[232:235], v165 offset:5120
	ds_read_b128 v[236:239], v165 offset:6144
	ds_read_b128 v[240:243], v165 offset:7168
	global_load_lds_dwordx4 v[162:163], off
	v_lshl_add_u64 v[162:163], s[22:23], 0, v[156:157]
	s_add_i32 m0, s31, 0xe000
	s_nop 0
	global_load_lds_dwordx4 v[162:163], off
	s_waitcnt vmcnt(8)
	s_waitcnt lgkmcnt(0)
	s_barrier
	s_setprio 1
	s_waitcnt lgkmcnt(0)
	v_mfma_f32_16x16x32_bf16 v[128:131], v[158:161], v[212:215], v[128:131]
	v_mfma_f32_16x16x32_bf16 v[124:127], v[170:173], v[212:215], v[124:127]
	v_mfma_f32_16x16x32_bf16 v[112:115], v[158:161], v[220:223], v[112:115]
	v_mfma_f32_16x16x32_bf16 v[108:111], v[170:173], v[220:223], v[108:111]
	v_mfma_f32_16x16x32_bf16 v[96:99], v[158:161], v[228:231], v[96:99]
	v_mfma_f32_16x16x32_bf16 v[92:95], v[170:173], v[228:231], v[92:95]
	v_mfma_f32_16x16x32_bf16 v[80:83], v[158:161], v[236:239], v[80:83]
	v_mfma_f32_16x16x32_bf16 v[76:79], v[170:173], v[236:239], v[76:79]
	v_mfma_f32_16x16x32_bf16 v[128:131], v[166:169], v[216:219], v[128:131]
	v_mfma_f32_16x16x32_bf16 v[124:127], v[174:177], v[216:219], v[124:127]
	v_mfma_f32_16x16x32_bf16 v[112:115], v[166:169], v[224:227], v[112:115]
	v_mfma_f32_16x16x32_bf16 v[108:111], v[174:177], v[224:227], v[108:111]
	v_mfma_f32_16x16x32_bf16 v[96:99], v[166:169], v[232:235], v[96:99]
	v_mfma_f32_16x16x32_bf16 v[92:95], v[174:177], v[232:235], v[92:95]
	v_mfma_f32_16x16x32_bf16 v[80:83], v[166:169], v[240:243], v[80:83]
	v_mfma_f32_16x16x32_bf16 v[76:79], v[174:177], v[240:243], v[76:79]
	v_mfma_f32_16x16x32_bf16 v[120:123], v[178:181], v[212:215], v[120:123]
	v_mfma_f32_16x16x32_bf16 v[116:119], v[186:189], v[212:215], v[116:119]
	v_mfma_f32_16x16x32_bf16 v[104:107], v[178:181], v[220:223], v[104:107]
	v_mfma_f32_16x16x32_bf16 v[100:103], v[186:189], v[220:223], v[100:103]
	v_mfma_f32_16x16x32_bf16 v[88:91], v[178:181], v[228:231], v[88:91]
	v_mfma_f32_16x16x32_bf16 v[84:87], v[186:189], v[228:231], v[84:87]
	v_mfma_f32_16x16x32_bf16 v[72:75], v[178:181], v[236:239], v[72:75]
	v_mfma_f32_16x16x32_bf16 v[68:71], v[186:189], v[236:239], v[68:71]
	v_mfma_f32_16x16x32_bf16 v[120:123], v[182:185], v[216:219], v[120:123]
	v_mfma_f32_16x16x32_bf16 v[116:119], v[190:193], v[216:219], v[116:119]
	v_mfma_f32_16x16x32_bf16 v[104:107], v[182:185], v[224:227], v[104:107]
	v_mfma_f32_16x16x32_bf16 v[100:103], v[190:193], v[224:227], v[100:103]
	v_mfma_f32_16x16x32_bf16 v[88:91], v[182:185], v[232:235], v[88:91]
	v_mfma_f32_16x16x32_bf16 v[84:87], v[190:193], v[232:235], v[84:87]
	v_mfma_f32_16x16x32_bf16 v[72:75], v[182:185], v[240:243], v[72:75]
	v_mfma_f32_16x16x32_bf16 v[68:71], v[190:193], v[240:243], v[68:71]
	s_setprio 0
	s_barrier
	s_add_i32 s75, s75, s30
	v_lshl_add_u64 v[162:163], s[24:25], 0, v[136:137]
	s_mov_b32 m0, s75
	ds_read_b128 v[212:215], v165 offset:16384
	ds_read_b128 v[216:219], v165 offset:17408
	ds_read_b128 v[220:223], v165 offset:18432
	ds_read_b128 v[224:227], v165 offset:19456
	ds_read_b128 v[228:231], v165 offset:20480
	ds_read_b128 v[232:235], v165 offset:21504
	ds_read_b128 v[236:239], v165 offset:22528
	ds_read_b128 v[240:243], v165 offset:23552
	global_load_lds_dwordx4 v[162:163], off
	s_add_i32 m0, s75, 0x2000
	s_add_u32 s76, s24, 0x200000
	v_lshl_add_u64 v[198:199], s[24:25], 0, v[132:133]
	s_addc_u32 s77, s25, 0
	s_add_i32 s75, s78, s30
	global_load_lds_dwordx4 v[198:199], off
	v_lshl_add_u64 v[244:245], s[76:77], 0, v[136:137]
	s_mov_b32 m0, s75
	v_lshl_add_u64 v[246:247], s[26:27], 0, v[134:135]
	global_load_lds_dwordx4 v[244:245], off
	v_lshl_add_u64 v[244:245], s[76:77], 0, v[132:133]
	s_add_i32 m0, s75, 0x2000
	s_nop 0
	global_load_lds_dwordx4 v[244:245], off
	v_lshl_add_u64 v[244:245], s[26:27], 0, v[138:139]
	s_mov_b32 m0, s31
	s_nop 0
	global_load_lds_dwordx4 v[244:245], off
	s_mov_b32 m0, s34
	s_nop 0
	global_load_lds_dwordx4 v[246:247], off
	s_waitcnt vmcnt(8)
	s_waitcnt lgkmcnt(0)
	s_barrier
; #define PG8_STAGE(bufoff, gbase, voff) do { _Pragma("unroll") for (int _i = 0; _i < 2; ++_i) \
;         __builtin_amdgcn_global_load_lds((const unsigned*)((const char*)(gbase) + (voff)[_i]), (LAS unsigned*)(lds + (bufoff) + ldsw + _i * 8192), 16, 0, 0); } while (0)
; #define PG8_LDA(dst, b, h) do { _Pragma("unroll") for (int m = 0; m < 4; ++m) _Pragma("unroll") for (int k = 0; k < 2; ++k) dst[m][k] = *(const LAS bf16x8*)(lds + PG8_SA(b, h) + aoff + m * 2048 + k * 1024); } while (0)
; #define PG8_LDB(dst, b, h) do { _Pragma("unroll") for (int n = 0; n < 2; ++n) _Pragma("unroll") for (int k = 0; k < 2; ++k) dst[n][k] = *(const LAS bf16x8*)(lds + PG8_SB(b, h) + boff + n * 2048 + k * 1024); } while (0)
; #define PG8_MMA(ai, bj, At, Bt) do { __builtin_amdgcn_s_setprio(1); _Pragma("unroll") for (int m = 0; m < 4; ++m) _Pragma("unroll") for (int n = 0; n < 2; ++n) _Pragma("unroll") for (int k = 0; k < 2; ++k) \
;         acc[ai][bj][m][n] = __builtin_amdgcn_mfma_f32_16x16x32_bf16(Bt[n][k], At[m][k], acc[ai][bj][m][n], 0, 0, 0); __builtin_amdgcn_s_setprio(0); } while (0)
; #define PG8_WAIT_V(n) asm volatile("s_waitcnt vmcnt(" #n ")" ::: "memory")
; #define PG8_WAIT_L(n) asm volatile("s_waitcnt lgkmcnt(" #n ")" ::: "memory")
; #define PG8_BAR __builtin_amdgcn_s_barrier()
; #define PG8_SCHED __builtin_amdgcn_sched_barrier(0)
; template <class Epi>
; __device__ __forceinline__ void gemm_phase(LAS unsigned char* lds, const Gemm g, const StaticOrder& S, const Epi& E) {
;     ...
;             PG8_LDA(At, 0, 1); PG8_STAGE(PG8_SB(0, 0), b2, voffB); PG8_STAGE(PG8_SB(0, 1), b2 + hstep, voffB); PG8_STAGE(PG8_SA(0, 0), a2, voffA);
;             PG8_WAIT_V(8); PG8_WAIT_L(0); PG8_BAR; PG8_MMA(1, 0, At, B0); PG8_MMA(1, 1, At, B1); PG8_BAR; PG8_SCHED;
;             PG8_LDB(B0, 1, 0); PG8_LDB(B1, 1, 1); PG8_SCHED; PG8_LDA(At, 1, 0); PG8_STAGE(PG8_SA(0, 1), a2 + hstep, voffA);
;             PG8_WAIT_V(8); PG8_WAIT_L(0); PG8_BAR; PG8_MMA(0, 0, At, B0); PG8_MMA(0, 1, At, B1); PG8_BAR; PG8_SCHED;
	s_setprio 1
	s_waitcnt lgkmcnt(0)
	v_mfma_f32_16x16x32_bf16 v[64:67], v[158:161], v[212:215], v[64:67]
	v_mfma_f32_16x16x32_bf16 v[60:63], v[170:173], v[212:215], v[60:63]
	v_mfma_f32_16x16x32_bf16 v[48:51], v[158:161], v[220:223], v[48:51]
	v_mfma_f32_16x16x32_bf16 v[44:47], v[170:173], v[220:223], v[44:47]
	v_mfma_f32_16x16x32_bf16 v[32:35], v[158:161], v[228:231], v[32:35]
	v_mfma_f32_16x16x32_bf16 v[28:31], v[170:173], v[228:231], v[28:31]
	v_mfma_f32_16x16x32_bf16 v[16:19], v[158:161], v[236:239], v[16:19]
	v_mfma_f32_16x16x32_bf16 v[12:15], v[170:173], v[236:239], v[12:15]
	v_mfma_f32_16x16x32_bf16 v[64:67], v[166:169], v[216:219], v[64:67]
	v_mfma_f32_16x16x32_bf16 v[60:63], v[174:177], v[216:219], v[60:63]
	v_mfma_f32_16x16x32_bf16 v[48:51], v[166:169], v[224:227], v[48:51]
	v_mfma_f32_16x16x32_bf16 v[44:47], v[174:177], v[224:227], v[44:47]
	v_mfma_f32_16x16x32_bf16 v[32:35], v[166:169], v[232:235], v[32:35]
	v_mfma_f32_16x16x32_bf16 v[28:31], v[174:177], v[232:235], v[28:31]
	v_mfma_f32_16x16x32_bf16 v[16:19], v[166:169], v[240:243], v[16:19]
	v_mfma_f32_16x16x32_bf16 v[12:15], v[174:177], v[240:243], v[12:15]
	v_mfma_f32_16x16x32_bf16 v[56:59], v[178:181], v[212:215], v[56:59]
	v_mfma_f32_16x16x32_bf16 v[52:55], v[186:189], v[212:215], v[52:55]
	v_mfma_f32_16x16x32_bf16 v[40:43], v[178:181], v[220:223], v[40:43]
	v_mfma_f32_16x16x32_bf16 v[36:39], v[186:189], v[220:223], v[36:39]
	v_mfma_f32_16x16x32_bf16 v[24:27], v[178:181], v[228:231], v[24:27]
	v_mfma_f32_16x16x32_bf16 v[20:23], v[186:189], v[228:231], v[20:23]
	v_mfma_f32_16x16x32_bf16 v[8:11], v[178:181], v[236:239], v[8:11]
	v_mfma_f32_16x16x32_bf16 v[4:7], v[186:189], v[236:239], v[4:7]
	v_mfma_f32_16x16x32_bf16 v[56:59], v[182:185], v[216:219], v[56:59]
	v_mfma_f32_16x16x32_bf16 v[52:55], v[190:193], v[216:219], v[52:55]
	v_mfma_f32_16x16x32_bf16 v[40:43], v[182:185], v[224:227], v[40:43]
	v_mfma_f32_16x16x32_bf16 v[36:39], v[190:193], v[224:227], v[36:39]
	v_mfma_f32_16x16x32_bf16 v[24:27], v[182:185], v[232:235], v[24:27]
	v_mfma_f32_16x16x32_bf16 v[20:23], v[190:193], v[232:235], v[20:23]
	v_mfma_f32_16x16x32_bf16 v[8:11], v[182:185], v[240:243], v[8:11]
	v_mfma_f32_16x16x32_bf16 v[4:7], v[190:193], v[240:243], v[4:7]
	s_setprio 0
	s_barrier
	s_add_i32 s75, 0, 0x18000
	s_add_i32 s76, 0, 0x1c000
	v_add_u32_e32 v174, s75, v147
	v_add_u32_e32 v190, s76, v147
	ds_read_b128 v[158:161], v174
	ds_read_b128 v[166:169], v174 offset:1024
	ds_read_b128 v[170:173], v174 offset:2048
	ds_read_b128 v[174:177], v174 offset:3072
	ds_read_b128 v[178:181], v190
	ds_read_b128 v[182:185], v190 offset:1024
	ds_read_b128 v[186:189], v190 offset:2048
	ds_read_b128 v[190:193], v190 offset:3072
	s_add_u32 s26, s26, 0x200000
	s_addc_u32 s27, s27, 0
	s_mov_b32 m0, s35
	v_lshl_add_u64 v[248:249], s[26:27], 0, v[138:139]
	ds_read_b128 v[212:215], v165 offset:32768
	ds_read_b128 v[216:219], v165 offset:33792
	ds_read_b128 v[220:223], v165 offset:34816
	ds_read_b128 v[224:227], v165 offset:35840
	ds_read_b128 v[228:231], v165 offset:36864
	ds_read_b128 v[232:235], v165 offset:37888
	ds_read_b128 v[236:239], v165 offset:38912
	ds_read_b128 v[240:243], v165 offset:39936
	global_load_lds_dwordx4 v[248:249], off
	v_lshl_add_u64 v[248:249], s[26:27], 0, v[134:135]
	s_mov_b32 m0, s36
	s_nop 0
	global_load_lds_dwordx4 v[248:249], off
	s_waitcnt vmcnt(8)
	s_waitcnt lgkmcnt(0)
	s_barrier
	s_setprio 1
	s_waitcnt lgkmcnt(0)
	v_mfma_f32_16x16x32_bf16 v[128:131], v[158:161], v[212:215], v[128:131]
	v_mfma_f32_16x16x32_bf16 v[124:127], v[170:173], v[212:215], v[124:127]
	v_mfma_f32_16x16x32_bf16 v[112:115], v[158:161], v[220:223], v[112:115]
	v_mfma_f32_16x16x32_bf16 v[108:111], v[170:173], v[220:223], v[108:111]
	v_mfma_f32_16x16x32_bf16 v[96:99], v[158:161], v[228:231], v[96:99]
	v_mfma_f32_16x16x32_bf16 v[92:95], v[170:173], v[228:231], v[92:95]
	v_mfma_f32_16x16x32_bf16 v[80:83], v[158:161], v[236:239], v[80:83]
	v_mfma_f32_16x16x32_bf16 v[76:79], v[170:173], v[236:239], v[76:79]
	v_mfma_f32_16x16x32_bf16 v[128:131], v[166:169], v[216:219], v[128:131]
	v_mfma_f32_16x16x32_bf16 v[124:127], v[174:177], v[216:219], v[124:127]
	v_mfma_f32_16x16x32_bf16 v[112:115], v[166:169], v[224:227], v[112:115]
	v_mfma_f32_16x16x32_bf16 v[108:111], v[174:177], v[224:227], v[108:111]
	v_mfma_f32_16x16x32_bf16 v[96:99], v[166:169], v[232:235], v[96:99]
	v_mfma_f32_16x16x32_bf16 v[92:95], v[174:177], v[232:235], v[92:95]
	v_mfma_f32_16x16x32_bf16 v[80:83], v[166:169], v[240:243], v[80:83]
	v_mfma_f32_16x16x32_bf16 v[76:79], v[174:177], v[240:243], v[76:79]
	v_mfma_f32_16x16x32_bf16 v[120:123], v[178:181], v[212:215], v[120:123]
	v_mfma_f32_16x16x32_bf16 v[116:119], v[186:189], v[212:215], v[116:119]
	v_mfma_f32_16x16x32_bf16 v[104:107], v[178:181], v[220:223], v[104:107]
	v_mfma_f32_16x16x32_bf16 v[100:103], v[186:189], v[220:223], v[100:103]
	v_mfma_f32_16x16x32_bf16 v[88:91], v[178:181], v[228:231], v[88:91]
	v_mfma_f32_16x16x32_bf16 v[84:87], v[186:189], v[228:231], v[84:87]
	v_mfma_f32_16x16x32_bf16 v[72:75], v[178:181], v[236:239], v[72:75]
	v_mfma_f32_16x16x32_bf16 v[68:71], v[186:189], v[236:239], v[68:71]
	v_mfma_f32_16x16x32_bf16 v[120:123], v[182:185], v[216:219], v[120:123]
	v_mfma_f32_16x16x32_bf16 v[116:119], v[190:193], v[216:219], v[116:119]
	v_mfma_f32_16x16x32_bf16 v[104:107], v[182:185], v[224:227], v[104:107]
	v_mfma_f32_16x16x32_bf16 v[100:103], v[190:193], v[224:227], v[100:103]
	v_mfma_f32_16x16x32_bf16 v[88:91], v[182:185], v[232:235], v[88:91]
	v_mfma_f32_16x16x32_bf16 v[84:87], v[190:193], v[232:235], v[84:87]
	v_mfma_f32_16x16x32_bf16 v[72:75], v[182:185], v[240:243], v[72:75]
	v_mfma_f32_16x16x32_bf16 v[68:71], v[190:193], v[240:243], v[68:71]
	s_setprio 0
	s_barrier
; #define PG8_STAGE(bufoff, gbase, voff) do { _Pragma("unroll") for (int _i = 0; _i < 2; ++_i) \
;         __builtin_amdgcn_global_load_lds((const unsigned*)((const char*)(gbase) + (voff)[_i]), (LAS unsigned*)(lds + (bufoff) + ldsw + _i * 8192), 16, 0, 0); } while (0)
; #define PG8_LDA(dst, b, h) do { _Pragma("unroll") for (int m = 0; m < 4; ++m) _Pragma("unroll") for (int k = 0; k < 2; ++k) dst[m][k] = *(const LAS bf16x8*)(lds + PG8_SA(b, h) + aoff + m * 2048 + k * 1024); } while (0)
; #define PG8_MMA(ai, bj, At, Bt) do { __builtin_amdgcn_s_setprio(1); _Pragma("unroll") for (int m = 0; m < 4; ++m) _Pragma("unroll") for (int n = 0; n < 2; ++n) _Pragma("unroll") for (int k = 0; k < 2; ++k) \
;         acc[ai][bj][m][n] = __builtin_amdgcn_mfma_f32_16x16x32_bf16(Bt[n][k], At[m][k], acc[ai][bj][m][n], 0, 0, 0); __builtin_amdgcn_s_setprio(0); } while (0)
; #define PG8_WAIT_V(n) asm volatile("s_waitcnt vmcnt(" #n ")" ::: "memory")
; #define PG8_WAIT_L(n) asm volatile("s_waitcnt lgkmcnt(" #n ")" ::: "memory")
; #define PG8_BAR __builtin_amdgcn_s_barrier()
; #define PG8_SCHED __builtin_amdgcn_sched_barrier(0)
; template <class Epi>
; __device__ __forceinline__ void gemm_phase(LAS unsigned char* lds, const Gemm g, const StaticOrder& S, const Epi& E) {
;     ...
;             PG8_LDA(At, 1, 1); PG8_STAGE(PG8_SB(1, 0), b3, voffB); PG8_STAGE(PG8_SB(1, 1), b3 + hstep, voffB); PG8_STAGE(PG8_SA(1, 0), a3, voffA);
;             PG8_WAIT_V(8); PG8_WAIT_L(0); PG8_BAR; PG8_MMA(1, 0, At, B0); PG8_MMA(1, 1, At, B1); PG8_BAR; PG8_SCHED;
;         }
	s_add_i32 s26, s75, s30
	v_lshl_add_u64 v[162:163], v[162:163], 0, s[68:69]
	s_mov_b32 m0, s26
	ds_read_b128 v[212:215], v165 offset:49152
	ds_read_b128 v[216:219], v165 offset:50176
	ds_read_b128 v[220:223], v165 offset:51200
	ds_read_b128 v[224:227], v165 offset:52224
	ds_read_b128 v[228:231], v165 offset:53248
	ds_read_b128 v[232:235], v165 offset:54272
	ds_read_b128 v[236:239], v165 offset:55296
	ds_read_b128 v[240:243], v165 offset:56320
	global_load_lds_dwordx4 v[162:163], off
	s_add_i32 m0, s26, 0x2000
	s_add_u32 s24, s24, 0x200080
	v_lshl_add_u64 v[162:163], v[198:199], 0, s[68:69]
	s_addc_u32 s25, s25, 0
	s_add_i32 s26, s76, s30
	global_load_lds_dwordx4 v[162:163], off
	v_lshl_add_u64 v[162:163], s[24:25], 0, v[136:137]
	s_mov_b32 m0, s26
	s_nop 0
	global_load_lds_dwordx4 v[162:163], off
	v_lshl_add_u64 v[162:163], s[24:25], 0, v[132:133]
	s_add_i32 m0, s26, 0x2000
	s_nop 0
	global_load_lds_dwordx4 v[162:163], off
	v_lshl_add_u64 v[162:163], v[244:245], 0, s[68:69]
	s_mov_b32 m0, s38
	s_nop 0
	global_load_lds_dwordx4 v[162:163], off
	v_lshl_add_u64 v[162:163], v[246:247], 0, s[68:69]
	s_mov_b32 m0, s39
	s_nop 0
	global_load_lds_dwordx4 v[162:163], off
	s_waitcnt vmcnt(8)
	s_waitcnt lgkmcnt(0)
	s_barrier
	s_setprio 1
	s_waitcnt lgkmcnt(0)
	v_mfma_f32_16x16x32_bf16 v[64:67], v[158:161], v[212:215], v[64:67]
	v_mfma_f32_16x16x32_bf16 v[60:63], v[170:173], v[212:215], v[60:63]
	v_mfma_f32_16x16x32_bf16 v[48:51], v[158:161], v[220:223], v[48:51]
	v_mfma_f32_16x16x32_bf16 v[44:47], v[170:173], v[220:223], v[44:47]
	v_mfma_f32_16x16x32_bf16 v[32:35], v[158:161], v[228:231], v[32:35]
	v_mfma_f32_16x16x32_bf16 v[28:31], v[170:173], v[228:231], v[28:31]
	v_mfma_f32_16x16x32_bf16 v[16:19], v[158:161], v[236:239], v[16:19]
	v_mfma_f32_16x16x32_bf16 v[12:15], v[170:173], v[236:239], v[12:15]
	v_mfma_f32_16x16x32_bf16 v[64:67], v[166:169], v[216:219], v[64:67]
	v_mfma_f32_16x16x32_bf16 v[60:63], v[174:177], v[216:219], v[60:63]
	v_mfma_f32_16x16x32_bf16 v[48:51], v[166:169], v[224:227], v[48:51]
	v_mfma_f32_16x16x32_bf16 v[44:47], v[174:177], v[224:227], v[44:47]
	v_mfma_f32_16x16x32_bf16 v[32:35], v[166:169], v[232:235], v[32:35]
	v_mfma_f32_16x16x32_bf16 v[28:31], v[174:177], v[232:235], v[28:31]
	v_mfma_f32_16x16x32_bf16 v[16:19], v[166:169], v[240:243], v[16:19]
	v_mfma_f32_16x16x32_bf16 v[12:15], v[174:177], v[240:243], v[12:15]
	v_mfma_f32_16x16x32_bf16 v[56:59], v[178:181], v[212:215], v[56:59]
	v_mfma_f32_16x16x32_bf16 v[52:55], v[186:189], v[212:215], v[52:55]
	v_mfma_f32_16x16x32_bf16 v[40:43], v[178:181], v[220:223], v[40:43]
	v_mfma_f32_16x16x32_bf16 v[36:39], v[186:189], v[220:223], v[36:39]
	v_mfma_f32_16x16x32_bf16 v[24:27], v[178:181], v[228:231], v[24:27]
	v_mfma_f32_16x16x32_bf16 v[20:23], v[186:189], v[228:231], v[20:23]
	v_mfma_f32_16x16x32_bf16 v[8:11], v[178:181], v[236:239], v[8:11]
	v_mfma_f32_16x16x32_bf16 v[4:7], v[186:189], v[236:239], v[4:7]
	v_mfma_f32_16x16x32_bf16 v[56:59], v[182:185], v[216:219], v[56:59]
	v_mfma_f32_16x16x32_bf16 v[52:55], v[190:193], v[216:219], v[52:55]
	v_mfma_f32_16x16x32_bf16 v[40:43], v[182:185], v[224:227], v[40:43]
	v_mfma_f32_16x16x32_bf16 v[36:39], v[190:193], v[224:227], v[36:39]
	v_mfma_f32_16x16x32_bf16 v[24:27], v[182:185], v[232:235], v[24:27]
	v_mfma_f32_16x16x32_bf16 v[20:23], v[190:193], v[232:235], v[20:23]
	v_mfma_f32_16x16x32_bf16 v[8:11], v[182:185], v[240:243], v[8:11]
	v_mfma_f32_16x16x32_bf16 v[4:7], v[190:193], v[240:243], v[4:7]
	s_setprio 0
	s_barrier
	s_add_i32 s74, s74, 2
	s_add_u32 s22, s22, 0x100
	s_addc_u32 s23, s23, 0
	s_add_u32 s60, s60, 0x100
	s_addc_u32 s61, s61, 0
	s_cmpk_gt_u32 s74, 0x7d
	s_cbranch_scc0 .LBB0_1972
	s_and_b64 vcc, exec, s[12:13]
	s_cbranch_vccz .LBB0_1975
	s_barrier
